# sample attention: coalesced L2 warm-up of the task's cached K/V rows before the dependent load chains
# speedup vs baseline: 1.0331x; 1.0012x over previous
.LBB0_459:
	v_lshrrev_b32_e32 v140, 4, v52
	v_and_b32_e32 v141, 15, v52
	v_lshlrev_b32_e32 v140, 10, v140
	v_lshl_add_u32 v140, v141, 4, v140
	v_ashrrev_i32_e32 v141, 2, v53
	v_lshl_add_u32 v140, v141, 17, v140
	v_and_b32_e32 v141, 3, v53
	v_lshl_add_u32 v140, v141, 8, v140
	v_mov_b32_e32 v141, 0
	v_readlane_b32 s0, v254, 20
	v_readlane_b32 s1, v254, 21
	s_nop 1
	v_lshl_add_u64 v[142:143], s[0:1], 0, v[140:141]
	v_mov_b32_e32 v144, 0x1000
	v_mov_b32_e32 v145, 0
	global_load_dwordx4 v[148:151], v[142:143], off
	v_lshl_add_u64 v[142:143], v[142:143], 0, v[144:145]
	global_load_dwordx4 v[148:151], v[142:143], off
	v_lshl_add_u64 v[142:143], v[142:143], 0, v[144:145]
	global_load_dwordx4 v[148:151], v[142:143], off
	v_lshl_add_u64 v[142:143], v[142:143], 0, v[144:145]
	global_load_dwordx4 v[148:151], v[142:143], off
	v_lshl_add_u64 v[142:143], v[142:143], 0, v[144:145]
	global_load_dwordx4 v[148:151], v[142:143], off
	v_lshl_add_u64 v[142:143], v[142:143], 0, v[144:145]
	global_load_dwordx4 v[148:151], v[142:143], off
	v_lshl_add_u64 v[142:143], v[142:143], 0, v[144:145]
	global_load_dwordx4 v[148:151], v[142:143], off
	v_lshl_add_u64 v[142:143], v[142:143], 0, v[144:145]
	global_load_dwordx4 v[148:151], v[142:143], off
	v_lshl_add_u64 v[142:143], v[142:143], 0, v[144:145]
	global_load_dwordx4 v[148:151], v[142:143], off
	v_lshl_add_u64 v[142:143], v[142:143], 0, v[144:145]
	global_load_dwordx4 v[148:151], v[142:143], off
	v_lshl_add_u64 v[142:143], v[142:143], 0, v[144:145]
	global_load_dwordx4 v[148:151], v[142:143], off
	v_lshl_add_u64 v[142:143], v[142:143], 0, v[144:145]
	global_load_dwordx4 v[148:151], v[142:143], off
	v_lshl_add_u64 v[142:143], v[142:143], 0, v[144:145]
	global_load_dwordx4 v[148:151], v[142:143], off
	v_lshl_add_u64 v[142:143], v[142:143], 0, v[144:145]
	global_load_dwordx4 v[148:151], v[142:143], off
	v_lshl_add_u64 v[142:143], v[142:143], 0, v[144:145]
	global_load_dwordx4 v[148:151], v[142:143], off
	v_lshl_add_u64 v[142:143], v[142:143], 0, v[144:145]
	global_load_dwordx4 v[148:151], v[142:143], off
	v_lshl_add_u64 v[142:143], v[142:143], 0, v[144:145]
	global_load_dwordx4 v[148:151], v[142:143], off
	v_lshl_add_u64 v[142:143], v[142:143], 0, v[144:145]
	global_load_dwordx4 v[148:151], v[142:143], off
	v_lshl_add_u64 v[142:143], v[142:143], 0, v[144:145]
	global_load_dwordx4 v[148:151], v[142:143], off
	v_lshl_add_u64 v[142:143], v[142:143], 0, v[144:145]
	global_load_dwordx4 v[148:151], v[142:143], off
	v_lshl_add_u64 v[142:143], v[142:143], 0, v[144:145]
	global_load_dwordx4 v[148:151], v[142:143], off
	v_lshl_add_u64 v[142:143], v[142:143], 0, v[144:145]
	global_load_dwordx4 v[148:151], v[142:143], off
	v_lshl_add_u64 v[142:143], v[142:143], 0, v[144:145]
	global_load_dwordx4 v[148:151], v[142:143], off
	v_lshl_add_u64 v[142:143], v[142:143], 0, v[144:145]
	global_load_dwordx4 v[148:151], v[142:143], off
	v_lshl_add_u64 v[142:143], v[142:143], 0, v[144:145]
	global_load_dwordx4 v[148:151], v[142:143], off
	v_lshl_add_u64 v[142:143], v[142:143], 0, v[144:145]
	global_load_dwordx4 v[148:151], v[142:143], off
	v_lshl_add_u64 v[142:143], v[142:143], 0, v[144:145]
	global_load_dwordx4 v[148:151], v[142:143], off
	v_lshl_add_u64 v[142:143], v[142:143], 0, v[144:145]
	global_load_dwordx4 v[148:151], v[142:143], off
	v_lshl_add_u64 v[142:143], v[142:143], 0, v[144:145]
	global_load_dwordx4 v[148:151], v[142:143], off
	v_lshl_add_u64 v[142:143], v[142:143], 0, v[144:145]
	global_load_dwordx4 v[148:151], v[142:143], off
	v_lshl_add_u64 v[142:143], v[142:143], 0, v[144:145]
	global_load_dwordx4 v[148:151], v[142:143], off
	v_lshl_add_u64 v[142:143], v[142:143], 0, v[144:145]
	global_load_dwordx4 v[148:151], v[142:143], off
	v_readlane_b32 s0, v254, 18
	v_readlane_b32 s1, v254, 19
	s_nop 1
	v_lshl_add_u64 v[142:143], s[0:1], 0, v[140:141]
	v_mov_b32_e32 v144, 0x1000
	v_mov_b32_e32 v145, 0
	global_load_dwordx4 v[148:151], v[142:143], off
	v_lshl_add_u64 v[142:143], v[142:143], 0, v[144:145]
	global_load_dwordx4 v[148:151], v[142:143], off
	v_lshl_add_u64 v[142:143], v[142:143], 0, v[144:145]
	global_load_dwordx4 v[148:151], v[142:143], off
	v_lshl_add_u64 v[142:143], v[142:143], 0, v[144:145]
	global_load_dwordx4 v[148:151], v[142:143], off
	v_lshl_add_u64 v[142:143], v[142:143], 0, v[144:145]
	global_load_dwordx4 v[148:151], v[142:143], off
	v_lshl_add_u64 v[142:143], v[142:143], 0, v[144:145]
	global_load_dwordx4 v[148:151], v[142:143], off
	v_lshl_add_u64 v[142:143], v[142:143], 0, v[144:145]
	global_load_dwordx4 v[148:151], v[142:143], off
	v_lshl_add_u64 v[142:143], v[142:143], 0, v[144:145]
	global_load_dwordx4 v[148:151], v[142:143], off
	v_lshl_add_u64 v[142:143], v[142:143], 0, v[144:145]
	global_load_dwordx4 v[148:151], v[142:143], off
	v_lshl_add_u64 v[142:143], v[142:143], 0, v[144:145]
	global_load_dwordx4 v[148:151], v[142:143], off
	v_lshl_add_u64 v[142:143], v[142:143], 0, v[144:145]
	global_load_dwordx4 v[148:151], v[142:143], off
	v_lshl_add_u64 v[142:143], v[142:143], 0, v[144:145]
	global_load_dwordx4 v[148:151], v[142:143], off
	v_lshl_add_u64 v[142:143], v[142:143], 0, v[144:145]
	global_load_dwordx4 v[148:151], v[142:143], off
	v_lshl_add_u64 v[142:143], v[142:143], 0, v[144:145]
	global_load_dwordx4 v[148:151], v[142:143], off
	v_lshl_add_u64 v[142:143], v[142:143], 0, v[144:145]
	global_load_dwordx4 v[148:151], v[142:143], off
	v_lshl_add_u64 v[142:143], v[142:143], 0, v[144:145]
	global_load_dwordx4 v[148:151], v[142:143], off
	v_lshl_add_u64 v[142:143], v[142:143], 0, v[144:145]
	global_load_dwordx4 v[148:151], v[142:143], off
	v_lshl_add_u64 v[142:143], v[142:143], 0, v[144:145]
	global_load_dwordx4 v[148:151], v[142:143], off
	v_lshl_add_u64 v[142:143], v[142:143], 0, v[144:145]
	global_load_dwordx4 v[148:151], v[142:143], off
	v_lshl_add_u64 v[142:143], v[142:143], 0, v[144:145]
	global_load_dwordx4 v[148:151], v[142:143], off
	v_lshl_add_u64 v[142:143], v[142:143], 0, v[144:145]
	global_load_dwordx4 v[148:151], v[142:143], off
	v_lshl_add_u64 v[142:143], v[142:143], 0, v[144:145]
	global_load_dwordx4 v[148:151], v[142:143], off
	v_lshl_add_u64 v[142:143], v[142:143], 0, v[144:145]
	global_load_dwordx4 v[148:151], v[142:143], off
	v_lshl_add_u64 v[142:143], v[142:143], 0, v[144:145]
	global_load_dwordx4 v[148:151], v[142:143], off
	v_lshl_add_u64 v[142:143], v[142:143], 0, v[144:145]
	global_load_dwordx4 v[148:151], v[142:143], off
	v_lshl_add_u64 v[142:143], v[142:143], 0, v[144:145]
	global_load_dwordx4 v[148:151], v[142:143], off
	v_lshl_add_u64 v[142:143], v[142:143], 0, v[144:145]
	global_load_dwordx4 v[148:151], v[142:143], off
	v_lshl_add_u64 v[142:143], v[142:143], 0, v[144:145]
	global_load_dwordx4 v[148:151], v[142:143], off
	v_lshl_add_u64 v[142:143], v[142:143], 0, v[144:145]
	global_load_dwordx4 v[148:151], v[142:143], off
	v_lshl_add_u64 v[142:143], v[142:143], 0, v[144:145]
	global_load_dwordx4 v[148:151], v[142:143], off
	v_lshl_add_u64 v[142:143], v[142:143], 0, v[144:145]
	global_load_dwordx4 v[148:151], v[142:143], off
	v_lshl_add_u64 v[142:143], v[142:143], 0, v[144:145]
	global_load_dwordx4 v[148:151], v[142:143], off
	v_ashrrev_i32_e32 v4, 2, v53
	v_add_u32_e32 v64, 0x2000, v4
	v_ashrrev_i32_e32 v65, 31, v64
	v_and_b32_e32 v63, 3, v53
	v_lshlrev_b64 v[0:1], 11, v[64:65]
	v_lshl_add_u64 v[0:1], s[2:3], 0, v[0:1]
	v_lshlrev_b32_e32 v2, 9, v63
	v_mov_b32_e32 v3, v55
	v_lshl_add_u64 v[0:1], v[0:1], 0, v[2:3]
	v_lshl_add_u64 v[0:1], v[0:1], 0, v[58:59]
	global_load_dwordx2 v[2:3], v[0:1], off
	v_lshlrev_b32_e32 v62, 7, v4
	v_readlane_b32 s36, v254, 14
	v_or_b32_e32 v0, v62, v52
	v_readlane_b32 s50, v254, 28
	v_readlane_b32 s51, v254, 29
	v_ashrrev_i32_e32 v1, 31, v0
	v_readlane_b32 s40, v254, 18
	v_readlane_b32 s41, v254, 19
	v_readlane_b32 s42, v254, 20
	v_readlane_b32 s43, v254, 21
	v_readlane_b32 s44, v254, 22
	v_readlane_b32 s45, v254, 23
	v_readlane_b32 s46, v254, 24
	v_readlane_b32 s47, v254, 25
	v_readlane_b32 s48, v254, 26
	v_readlane_b32 s49, v254, 27
	s_mov_b64 s[66:67], s[50:51]
	v_lshlrev_b64 v[0:1], 10, v[0:1]
	s_mov_b64 s[56:57], s[40:41]
	v_lshlrev_b32_e32 v54, 8, v63
	v_lshl_add_u64 v[0:1], s[56:57], 0, v[0:1]
	v_readlane_b32 s37, v254, 15
	v_readlane_b32 s38, v254, 16
	v_readlane_b32 s39, v254, 17
	v_lshl_add_u64 v[16:17], v[0:1], 0, v[54:55]
	s_mov_b64 s[64:65], s[48:49]
	s_mov_b64 s[62:63], s[46:47]
	s_mov_b64 s[60:61], s[44:45]
	s_mov_b64 s[58:59], s[42:43]
	v_readlane_b32 s36, v254, 30
	v_readlane_b32 s40, v254, 34
	v_readlane_b32 s41, v254, 35
	v_lshlrev_b64 v[60:61], 10, v[64:65]
	v_and_b32_e32 v88, 3, v73
	v_readlane_b32 s37, v254, 31
	v_readlane_b32 s38, v254, 32
	v_readlane_b32 s39, v254, 33
	v_readlane_b32 s42, v254, 36
	v_readlane_b32 s43, v254, 37
	v_readlane_b32 s44, v254, 38
	v_readlane_b32 s45, v254, 39
	v_readlane_b32 s46, v254, 40
	v_readlane_b32 s47, v254, 41
	v_readlane_b32 s48, v254, 42
	v_readlane_b32 s49, v254, 43
	v_readlane_b32 s50, v254, 44
	v_readlane_b32 s51, v254, 45
	s_waitcnt vmcnt(0)
	v_lshlrev_b32_e32 v0, 16, v2
	v_and_b32_e32 v1, 0xffff0000, v2
	v_lshlrev_b32_e32 v2, 16, v3
	v_and_b32_e32 v3, 0xffff0000, v3
	ds_write_b128 v67, v[0:3]
	v_lshlrev_b32_e32 v0, 2, v63
	s_waitcnt lgkmcnt(0)
	v_lshlrev_b32_e32 v1, 4, v63
	v_or_b32_e32 v2, 1, v0
	v_or_b32_e32 v3, 2, v0
	v_or_b32_e32 v4, 3, v0
	v_add_u32_e32 v0, 4, v0
	global_load_dwordx4 v[94:97], v[16:17], off nt
	global_load_dwordx4 v[98:101], v[16:17], off offset:16 nt
	v_cvt_f32_ubyte0_e32 v89, v2
	v_cvt_f32_ubyte0_e32 v90, v3
	v_cvt_f32_ubyte0_e32 v91, v4
	v_cvt_f32_ubyte0_e32 v92, v0
	global_load_dwordx4 v[0:3], v1, s[40:41]
	s_nop 0
	global_load_dwordx4 v[102:105], v[16:17], off offset:48 nt
	global_load_dwordx4 v[106:109], v[16:17], off offset:32 nt
	global_load_dwordx4 v[36:39], v[16:17], off offset:112 nt
	global_load_dwordx4 v[40:43], v[16:17], off offset:96 nt
	global_load_dwordx4 v[44:47], v[16:17], off offset:80 nt
	global_load_dwordx4 v[48:51], v[16:17], off offset:64 nt
	global_load_dwordx4 v[20:23], v[16:17], off offset:176 nt
	global_load_dwordx4 v[24:27], v[16:17], off offset:160 nt
	global_load_dwordx4 v[28:31], v[16:17], off offset:144 nt
	global_load_dwordx4 v[32:35], v[16:17], off offset:128 nt
	global_load_dwordx4 v[4:7], v[16:17], off offset:240 nt
	global_load_dwordx4 v[8:11], v[16:17], off offset:224 nt
	global_load_dwordx4 v[12:15], v[16:17], off offset:208 nt
	s_nop 0
	global_load_dwordx4 v[16:19], v[16:17], off offset:192 nt
	v_mul_f32_e32 v110, -0.5, v90
	v_mul_f32_e32 v111, -0.5, v91
	v_mul_f32_e32 v112, -0.5, v92
	v_cmp_gt_f32_e64 s[0:1], s21, v110
	v_cmp_gt_f32_e64 s[6:7], s21, v111
	v_cmp_gt_f32_e64 s[8:9], s21, v112
	v_cndmask_b32_e64 v110, 0, v74, s[0:1]
	v_cndmask_b32_e64 v111, 0, v74, s[6:7]
	v_cndmask_b32_e64 v112, 0, v74, s[8:9]
	v_fmac_f32_e32 v110, -0.5, v90
	v_fmac_f32_e32 v111, -0.5, v91
	v_fmac_f32_e32 v112, -0.5, v92
	v_mul_f32_e32 v93, -0.5, v89
	v_exp_f32_e32 v110, v110
	v_exp_f32_e32 v111, v111
	v_exp_f32_e32 v112, v112
	v_cmp_gt_f32_e32 vcc, s21, v93
	v_cndmask_b32_e64 v90, 0, v75, s[0:1]
	v_cndmask_b32_e64 v91, 0, v75, s[6:7]
	v_cndmask_b32_e32 v93, 0, v74, vcc
	v_fmac_f32_e32 v93, -0.5, v89
	v_cndmask_b32_e64 v92, 0, v75, s[8:9]
	v_exp_f32_e32 v93, v93
	v_ldexp_f32 v90, v110, v90
	v_ldexp_f32 v91, v111, v91
	v_ldexp_f32 v92, v112, v92
	ds_read_b128 v[110:113], v66
	ds_read_b128 v[114:117], v66 offset:16
	ds_read_b128 v[118:121], v66 offset:256
	ds_read_b128 v[122:125], v66 offset:768
	ds_read_b128 v[126:129], v66 offset:784
	ds_read_b128 v[130:133], v66 offset:512
	ds_read_b128 v[134:137], v66 offset:528
	ds_read_b128 v[138:141], v66 offset:272
	v_cndmask_b32_e32 v89, 0, v75, vcc
	v_ldexp_f32 v89, v93, v89
	s_waitcnt vmcnt(0) lgkmcnt(0)
	v_mul_f32_e32 v93, v95, v111
	v_mul_f32_e32 v111, v97, v113
	s_waitcnt lgkmcnt(5)
	v_mul_f32_e32 v113, v95, v119
	v_mul_f32_e32 v119, v97, v121
	s_waitcnt lgkmcnt(2)
	v_mul_f32_e32 v121, v95, v131
	v_mul_f32_e32 v131, v97, v133
	v_mul_f32_e32 v95, v95, v123
	v_mul_f32_e32 v97, v97, v125
	s_waitcnt vmcnt(15)
	v_mul_f32_e32 v115, v99, v115
	v_mul_f32_e32 v117, v101, v117
	s_waitcnt lgkmcnt(0)
	v_mul_f32_e32 v123, v99, v139
	v_mul_f32_e32 v125, v101, v141
	v_mul_f32_e32 v133, v99, v135
	v_mul_f32_e32 v135, v101, v137
	v_mul_f32_e32 v99, v99, v127
	v_mul_f32_e32 v101, v101, v129
	v_fmac_f32_e32 v93, v94, v110
	v_fmac_f32_e32 v111, v96, v112
	v_fmac_f32_e32 v113, v94, v118
	v_fmac_f32_e32 v119, v96, v120
	v_fmac_f32_e32 v121, v94, v130
	v_fmac_f32_e32 v131, v96, v132
	v_fmac_f32_e32 v95, v94, v122
	v_fmac_f32_e32 v97, v96, v124
	v_fmac_f32_e32 v115, v98, v114
	v_fmac_f32_e32 v117, v100, v116
	v_fmac_f32_e32 v123, v98, v138
	v_fmac_f32_e32 v125, v100, v140
	v_fmac_f32_e32 v133, v98, v134
	v_fmac_f32_e32 v135, v100, v136
	v_fmac_f32_e32 v99, v98, v126
	v_fmac_f32_e32 v101, v100, v128
	v_add_f32_e32 v93, v93, v111
	v_add_f32_e32 v94, v113, v119
	v_add_f32_e32 v96, v121, v131
	v_add_f32_e32 v95, v95, v97
	v_add_f32_e32 v97, v115, v117
	v_add_f32_e32 v98, v123, v125
	v_add_f32_e32 v100, v133, v135
	v_add_f32_e32 v99, v99, v101
	v_add_f32_e32 v93, 0, v93
	v_add_f32_e32 v94, 0, v94
	v_add_f32_e32 v96, 0, v96
	v_add_f32_e32 v95, 0, v95
	v_add_f32_e32 v93, v93, v97
	v_add_f32_e32 v118, v94, v98
	v_add_f32_e32 v122, v96, v100
	v_add_f32_e32 v123, v95, v99
	ds_read_b128 v[94:97], v66 offset:32
	ds_read_b128 v[98:101], v66 offset:48
	ds_read_b128 v[110:113], v66 offset:288
	ds_read_b128 v[114:117], v66 offset:544
	s_waitcnt vmcnt(12) lgkmcnt(3)
	v_mul_f32_e32 v95, v107, v95
	v_mul_f32_e32 v97, v109, v97
	v_fmac_f32_e32 v95, v106, v94
	v_fmac_f32_e32 v97, v108, v96
	v_add_f32_e32 v94, v95, v97
	v_add_f32_e32 v93, v93, v94
	ds_read_b128 v[94:97], v66 offset:304
	s_waitcnt lgkmcnt(2)
	v_mul_f32_e32 v111, v107, v111
	v_fmac_f32_e32 v111, v106, v110
	v_mul_f32_e32 v110, v109, v113
	v_fmac_f32_e32 v110, v108, v112
	v_add_f32_e32 v110, v111, v110
	v_add_f32_e32 v124, v118, v110
	ds_read_b128 v[110:113], v66 offset:560
	ds_read_b128 v[118:121], v66 offset:800
	s_waitcnt lgkmcnt(3)
	v_mul_f32_e32 v115, v107, v115
	v_fmac_f32_e32 v115, v106, v114
	v_mul_f32_e32 v114, v109, v117
	v_fmac_f32_e32 v114, v108, v116
	s_waitcnt lgkmcnt(2)
	v_mul_f32_e32 v95, v103, v95
	v_add_f32_e32 v114, v115, v114
	v_fmac_f32_e32 v95, v102, v94
	v_mul_f32_e32 v94, v105, v97
	v_add_f32_e32 v122, v122, v114
	ds_read_b128 v[114:117], v66 offset:816
	v_fmac_f32_e32 v94, v104, v96
	s_waitcnt lgkmcnt(1)
	v_mul_f32_e32 v107, v107, v119
	v_add_f32_e32 v94, v95, v94
	v_fmac_f32_e32 v107, v106, v118
	v_add_f32_e32 v118, v124, v94
	v_mul_f32_e32 v94, v103, v111
	v_mul_f32_e32 v95, v105, v113
	v_fmac_f32_e32 v94, v102, v110
	v_fmac_f32_e32 v95, v104, v112
	v_mul_f32_e32 v106, v109, v121
	v_mul_f32_e32 v99, v103, v99
	v_add_f32_e32 v94, v94, v95
	v_fmac_f32_e32 v106, v108, v120
	v_fmac_f32_e32 v99, v102, v98
	v_mul_f32_e32 v98, v105, v101
	v_add_f32_e32 v119, v122, v94
	s_waitcnt lgkmcnt(0)
	v_mul_f32_e32 v94, v103, v115
	v_mul_f32_e32 v95, v105, v117
	v_add_f32_e32 v106, v107, v106
	v_fmac_f32_e32 v98, v104, v100
	v_fmac_f32_e32 v94, v102, v114
	v_fmac_f32_e32 v95, v104, v116
	v_add_f32_e32 v106, v123, v106
	v_add_f32_e32 v98, v99, v98
	v_add_f32_e32 v94, v94, v95
	v_add_f32_e32 v93, v93, v98
	v_add_f32_e32 v114, v106, v94
	ds_read_b128 v[94:97], v66 offset:64
	ds_read_b128 v[98:101], v66 offset:80
	ds_read_b128 v[102:105], v66 offset:320
	ds_read_b128 v[106:109], v66 offset:576
	ds_read_b128 v[110:113], v66 offset:832
	s_waitcnt vmcnt(8) lgkmcnt(4)
	v_mul_f32_e32 v95, v49, v95
	v_mul_f32_e32 v97, v51, v97
	s_waitcnt lgkmcnt(2)
	v_mul_f32_e32 v103, v49, v103
	v_fmac_f32_e32 v103, v48, v102
	v_mul_f32_e32 v102, v51, v105
	v_fmac_f32_e32 v95, v48, v94
	v_fmac_f32_e32 v97, v50, v96
	v_fmac_f32_e32 v102, v50, v104
	v_add_f32_e32 v94, v95, v97
	v_add_f32_e32 v102, v103, v102
	v_add_f32_e32 v93, v93, v94
	ds_read_b128 v[94:97], v66 offset:336
	v_add_f32_e32 v115, v118, v102
	ds_read_b128 v[102:105], v66 offset:592
	s_waitcnt lgkmcnt(3)
	v_mul_f32_e32 v107, v49, v107
	s_waitcnt lgkmcnt(2)
	v_mul_f32_e32 v49, v49, v111
	v_fmac_f32_e32 v107, v48, v106
	v_mul_f32_e32 v106, v51, v109
	v_fmac_f32_e32 v49, v48, v110
	v_mul_f32_e32 v48, v51, v113
	v_fmac_f32_e32 v106, v50, v108
	v_fmac_f32_e32 v48, v50, v112
	v_add_f32_e32 v106, v107, v106
	v_add_f32_e32 v48, v49, v48
	v_mul_f32_e32 v49, v45, v99
	v_mul_f32_e32 v50, v47, v101
	v_add_f32_e32 v116, v119, v106
	ds_read_b128 v[106:109], v66 offset:848
	v_fmac_f32_e32 v49, v44, v98
	v_fmac_f32_e32 v50, v46, v100
	v_add_f32_e32 v49, v49, v50
	v_add_f32_e32 v93, v93, v49
	s_waitcnt lgkmcnt(2)
	v_mul_f32_e32 v49, v45, v95
	v_mul_f32_e32 v50, v47, v97
	v_fmac_f32_e32 v49, v44, v94
	v_fmac_f32_e32 v50, v46, v96
	v_add_f32_e32 v49, v49, v50
	v_add_f32_e32 v110, v115, v49
	s_waitcnt lgkmcnt(1)
	v_mul_f32_e32 v49, v45, v103
	s_waitcnt lgkmcnt(0)
	v_mul_f32_e32 v45, v45, v107
	v_fmac_f32_e32 v49, v44, v102
	v_mul_f32_e32 v50, v47, v105
	v_fmac_f32_e32 v45, v44, v106
	v_mul_f32_e32 v44, v47, v109
	v_fmac_f32_e32 v50, v46, v104
	v_fmac_f32_e32 v44, v46, v108
	v_add_f32_e32 v48, v114, v48
	v_add_f32_e32 v49, v49, v50
	v_add_f32_e32 v44, v45, v44
	v_add_f32_e32 v111, v116, v49
	v_add_f32_e32 v106, v48, v44
	ds_read_b128 v[44:47], v66 offset:96
	ds_read_b128 v[48:51], v66 offset:112
	ds_read_b128 v[94:97], v66 offset:352
	ds_read_b128 v[98:101], v66 offset:608
	ds_read_b128 v[102:105], v66 offset:864
	s_waitcnt lgkmcnt(4)
	v_mul_f32_e32 v45, v41, v45
	v_mul_f32_e32 v47, v43, v47
	s_waitcnt lgkmcnt(2)
	v_mul_f32_e32 v95, v41, v95
	v_fmac_f32_e32 v95, v40, v94
	v_mul_f32_e32 v94, v43, v97
	v_fmac_f32_e32 v45, v40, v44
	v_fmac_f32_e32 v47, v42, v46
	v_fmac_f32_e32 v94, v42, v96
	v_add_f32_e32 v44, v45, v47
	v_add_f32_e32 v94, v95, v94
	v_add_f32_e32 v93, v93, v44
	ds_read_b128 v[44:47], v66 offset:368
	v_add_f32_e32 v107, v110, v94
	ds_read_b128 v[94:97], v66 offset:624
	s_waitcnt lgkmcnt(3)
	v_mul_f32_e32 v99, v41, v99
	s_waitcnt lgkmcnt(2)
	v_mul_f32_e32 v41, v41, v103
	v_fmac_f32_e32 v99, v40, v98
	v_mul_f32_e32 v98, v43, v101
	v_fmac_f32_e32 v41, v40, v102
	v_mul_f32_e32 v40, v43, v105
	v_fmac_f32_e32 v98, v42, v100
	v_fmac_f32_e32 v40, v42, v104
	v_add_f32_e32 v98, v99, v98
	v_add_f32_e32 v40, v41, v40
	v_mul_f32_e32 v41, v37, v49
	v_mul_f32_e32 v42, v39, v51
	v_add_f32_e32 v108, v111, v98
	ds_read_b128 v[98:101], v66 offset:880
	v_fmac_f32_e32 v41, v36, v48
	v_fmac_f32_e32 v42, v38, v50
	v_add_f32_e32 v41, v41, v42
	v_add_f32_e32 v48, v93, v41
	s_waitcnt lgkmcnt(2)
	v_mul_f32_e32 v41, v37, v45
	v_mul_f32_e32 v42, v39, v47
	v_fmac_f32_e32 v41, v36, v44
	v_fmac_f32_e32 v42, v38, v46
	v_add_f32_e32 v41, v41, v42
	v_add_f32_e32 v93, v107, v41
	s_waitcnt lgkmcnt(1)
	v_mul_f32_e32 v41, v37, v95
	s_waitcnt lgkmcnt(0)
	v_mul_f32_e32 v37, v37, v99
	v_fmac_f32_e32 v41, v36, v94
	v_mul_f32_e32 v42, v39, v97
	v_fmac_f32_e32 v37, v36, v98
	v_mul_f32_e32 v36, v39, v101
	v_fmac_f32_e32 v42, v38, v96
	v_fmac_f32_e32 v36, v38, v100
	v_add_f32_e32 v40, v106, v40
	v_add_f32_e32 v41, v41, v42
	v_add_f32_e32 v36, v37, v36
	v_add_f32_e32 v102, v108, v41
	v_add_f32_e32 v98, v40, v36
	ds_read_b128 v[36:39], v66 offset:128
	ds_read_b128 v[40:43], v66 offset:144
	ds_read_b128 v[44:47], v66 offset:384
	ds_read_b128 v[94:97], v66 offset:896
	s_waitcnt vmcnt(4) lgkmcnt(3)
	v_mul_f32_e32 v37, v33, v37
	v_mul_f32_e32 v39, v35, v39
	s_waitcnt lgkmcnt(1)
	v_mul_f32_e32 v45, v33, v45
	v_fmac_f32_e32 v45, v32, v44
	v_mul_f32_e32 v44, v35, v47
	v_fmac_f32_e32 v37, v32, v36
	v_fmac_f32_e32 v39, v34, v38
	v_fmac_f32_e32 v44, v34, v46
	v_add_f32_e32 v36, v37, v39
	v_add_f32_e32 v44, v45, v44
	v_add_f32_e32 v99, v48, v36
	ds_read_b128 v[36:39], v66 offset:400
	ds_read_b128 v[48:51], v66 offset:640
	v_add_f32_e32 v93, v93, v44
	ds_read_b128 v[44:47], v66 offset:656
	s_waitcnt lgkmcnt(1)
	v_mul_f32_e32 v49, v33, v49
	v_mul_f32_e32 v33, v33, v95
	v_fmac_f32_e32 v49, v32, v48
	v_mul_f32_e32 v48, v35, v51
	v_fmac_f32_e32 v33, v32, v94
	v_mul_f32_e32 v32, v35, v97
	v_fmac_f32_e32 v48, v34, v50
	v_fmac_f32_e32 v32, v34, v96
	v_add_f32_e32 v48, v49, v48
	v_add_f32_e32 v32, v33, v32
	v_mul_f32_e32 v33, v29, v41
	v_mul_f32_e32 v34, v31, v43
	v_add_f32_e32 v100, v102, v48
	ds_read_b128 v[48:51], v66 offset:912
	v_fmac_f32_e32 v33, v28, v40
	v_fmac_f32_e32 v34, v30, v42
	v_add_f32_e32 v33, v33, v34
	v_add_f32_e32 v40, v99, v33
	v_mul_f32_e32 v33, v29, v37
	v_mul_f32_e32 v34, v31, v39
	v_fmac_f32_e32 v33, v28, v36
	v_fmac_f32_e32 v34, v30, v38
	v_add_f32_e32 v33, v33, v34
	v_add_f32_e32 v93, v93, v33
	s_waitcnt lgkmcnt(1)
	v_mul_f32_e32 v33, v29, v45
	s_waitcnt lgkmcnt(0)
	v_mul_f32_e32 v29, v29, v49
	v_fmac_f32_e32 v33, v28, v44
	v_mul_f32_e32 v34, v31, v47
	v_fmac_f32_e32 v29, v28, v48
	v_mul_f32_e32 v28, v31, v51
	v_fmac_f32_e32 v34, v30, v46
	v_fmac_f32_e32 v28, v30, v50
	v_add_f32_e32 v32, v98, v32
	v_add_f32_e32 v33, v33, v34
	v_add_f32_e32 v28, v29, v28
	v_add_f32_e32 v94, v100, v33
	v_add_f32_e32 v48, v32, v28
	ds_read_b128 v[28:31], v66 offset:160
	ds_read_b128 v[32:35], v66 offset:176
	ds_read_b128 v[36:39], v66 offset:416
	ds_read_b128 v[44:47], v66 offset:928
	s_waitcnt lgkmcnt(3)
	v_mul_f32_e32 v29, v25, v29
	v_mul_f32_e32 v31, v27, v31
	s_waitcnt lgkmcnt(1)
	v_mul_f32_e32 v37, v25, v37
	v_fmac_f32_e32 v37, v24, v36
	v_mul_f32_e32 v36, v27, v39
	v_fmac_f32_e32 v29, v24, v28
	v_fmac_f32_e32 v31, v26, v30
	v_fmac_f32_e32 v36, v26, v38
	v_add_f32_e32 v28, v29, v31
	v_add_f32_e32 v36, v37, v36
	v_add_f32_e32 v49, v40, v28
	ds_read_b128 v[28:31], v66 offset:432
	ds_read_b128 v[40:43], v66 offset:672
	v_add_f32_e32 v50, v93, v36
	ds_read_b128 v[36:39], v66 offset:688
	s_waitcnt lgkmcnt(1)
	v_mul_f32_e32 v41, v25, v41
	v_mul_f32_e32 v25, v25, v45
	v_fmac_f32_e32 v41, v24, v40
	v_mul_f32_e32 v40, v27, v43
	v_fmac_f32_e32 v25, v24, v44
	v_mul_f32_e32 v24, v27, v47
	v_fmac_f32_e32 v40, v26, v42
	v_fmac_f32_e32 v24, v26, v46
	v_add_f32_e32 v40, v41, v40
	v_add_f32_e32 v24, v25, v24
	v_mul_f32_e32 v25, v21, v33
	v_mul_f32_e32 v26, v23, v35
	v_add_f32_e32 v51, v94, v40
	ds_read_b128 v[40:43], v66 offset:944
	v_fmac_f32_e32 v25, v20, v32
	v_fmac_f32_e32 v26, v22, v34
	v_add_f32_e32 v25, v25, v26
	v_add_f32_e32 v32, v49, v25
	v_mul_f32_e32 v25, v21, v29
	v_mul_f32_e32 v26, v23, v31
	v_fmac_f32_e32 v25, v20, v28
	v_fmac_f32_e32 v26, v22, v30
	v_add_f32_e32 v25, v25, v26
	v_add_f32_e32 v44, v50, v25
	s_waitcnt lgkmcnt(1)
	v_mul_f32_e32 v25, v21, v37
	s_waitcnt lgkmcnt(0)
	v_mul_f32_e32 v21, v21, v41
	v_fmac_f32_e32 v25, v20, v36
	v_mul_f32_e32 v26, v23, v39
	v_fmac_f32_e32 v21, v20, v40
	v_mul_f32_e32 v20, v23, v43
	v_fmac_f32_e32 v26, v22, v38
	v_fmac_f32_e32 v20, v22, v42
	v_add_f32_e32 v24, v48, v24
	v_add_f32_e32 v25, v25, v26
	v_add_f32_e32 v20, v21, v20
	v_add_f32_e32 v45, v51, v25
	v_add_f32_e32 v40, v24, v20
	ds_read_b128 v[20:23], v66 offset:192
	ds_read_b128 v[24:27], v66 offset:208
	ds_read_b128 v[28:31], v66 offset:448
	ds_read_b128 v[36:39], v66 offset:960
	s_waitcnt vmcnt(0) lgkmcnt(3)
	v_mul_f32_e32 v21, v17, v21
	v_mul_f32_e32 v23, v19, v23
	s_waitcnt lgkmcnt(1)
	v_mul_f32_e32 v29, v17, v29
	v_fmac_f32_e32 v29, v16, v28
	v_mul_f32_e32 v28, v19, v31
	v_fmac_f32_e32 v21, v16, v20
	v_fmac_f32_e32 v23, v18, v22
	v_fmac_f32_e32 v28, v18, v30
	v_add_f32_e32 v20, v21, v23
	v_add_f32_e32 v28, v29, v28
	v_add_f32_e32 v41, v32, v20
	ds_read_b128 v[20:23], v66 offset:464
	ds_read_b128 v[32:35], v66 offset:704
	v_add_f32_e32 v42, v44, v28
	ds_read_b128 v[28:31], v66 offset:720
	s_waitcnt lgkmcnt(1)
	v_mul_f32_e32 v33, v17, v33
	v_mul_f32_e32 v17, v17, v37
	v_fmac_f32_e32 v33, v16, v32
	v_mul_f32_e32 v32, v19, v35
	v_fmac_f32_e32 v17, v16, v36
	v_mul_f32_e32 v16, v19, v39
	v_fmac_f32_e32 v32, v18, v34
	v_fmac_f32_e32 v16, v18, v38
	v_add_f32_e32 v32, v33, v32
	v_add_f32_e32 v16, v17, v16
	v_mul_f32_e32 v17, v13, v25
	v_mul_f32_e32 v18, v15, v27
	v_add_f32_e32 v43, v45, v32
	ds_read_b128 v[32:35], v66 offset:976
	v_fmac_f32_e32 v17, v12, v24
	v_fmac_f32_e32 v18, v14, v26
	v_add_f32_e32 v17, v17, v18
	v_add_f32_e32 v24, v41, v17
	v_mul_f32_e32 v17, v13, v21
	v_mul_f32_e32 v18, v15, v23
	v_fmac_f32_e32 v17, v12, v20
	v_fmac_f32_e32 v18, v14, v22
	v_add_f32_e32 v17, v17, v18
	v_add_f32_e32 v36, v42, v17
	s_waitcnt lgkmcnt(1)
	v_mul_f32_e32 v17, v13, v29
	s_waitcnt lgkmcnt(0)
	v_mul_f32_e32 v13, v13, v33
	v_fmac_f32_e32 v17, v12, v28
	v_mul_f32_e32 v18, v15, v31
	v_fmac_f32_e32 v13, v12, v32
	v_mul_f32_e32 v12, v15, v35
	v_fmac_f32_e32 v18, v14, v30
	v_fmac_f32_e32 v12, v14, v34
	v_add_f32_e32 v16, v40, v16
	v_add_f32_e32 v17, v17, v18
	v_add_f32_e32 v12, v13, v12
	v_add_f32_e32 v37, v43, v17
	v_add_f32_e32 v32, v16, v12
	ds_read_b128 v[12:15], v66 offset:224
	ds_read_b128 v[16:19], v66 offset:240
	ds_read_b128 v[20:23], v66 offset:480
	ds_read_b128 v[28:31], v66 offset:992
	s_waitcnt lgkmcnt(3)
	v_mul_f32_e32 v13, v9, v13
	v_mul_f32_e32 v15, v11, v15
	s_waitcnt lgkmcnt(1)
	v_mul_f32_e32 v21, v9, v21
	v_fmac_f32_e32 v21, v8, v20
	v_mul_f32_e32 v20, v11, v23
	v_fmac_f32_e32 v13, v8, v12
	v_fmac_f32_e32 v15, v10, v14
	v_fmac_f32_e32 v20, v10, v22
	v_add_f32_e32 v12, v13, v15
	v_add_f32_e32 v20, v21, v20
	v_add_f32_e32 v33, v24, v12
	ds_read_b128 v[12:15], v66 offset:496
	ds_read_b128 v[24:27], v66 offset:736
	v_add_f32_e32 v34, v36, v20
	ds_read_b128 v[20:23], v66 offset:752
	s_waitcnt lgkmcnt(1)
	v_mul_f32_e32 v25, v9, v25
	v_mul_f32_e32 v9, v9, v29
	v_fmac_f32_e32 v25, v8, v24
	v_mul_f32_e32 v24, v11, v27
	v_fmac_f32_e32 v9, v8, v28
	v_mul_f32_e32 v8, v11, v31
	v_fmac_f32_e32 v24, v10, v26
	v_fmac_f32_e32 v8, v10, v30
	v_add_f32_e32 v24, v25, v24
	v_add_f32_e32 v8, v9, v8
	v_mul_f32_e32 v9, v5, v17
	v_mul_f32_e32 v10, v7, v19
	v_add_f32_e32 v35, v37, v24
	ds_read_b128 v[24:27], v66 offset:1008
	v_fmac_f32_e32 v9, v4, v16
	v_fmac_f32_e32 v10, v6, v18
	v_add_f32_e32 v9, v9, v10
	v_add_f32_e32 v93, v33, v9
	v_mul_f32_e32 v9, v5, v13
	v_mul_f32_e32 v10, v7, v15
	v_fmac_f32_e32 v9, v4, v12
	v_fmac_f32_e32 v10, v6, v14
	v_add_f32_e32 v9, v9, v10
	v_add_f32_e32 v94, v34, v9
	s_waitcnt lgkmcnt(1)
	v_mul_f32_e32 v9, v5, v21
	s_waitcnt lgkmcnt(0)
	v_mul_f32_e32 v5, v5, v25
	v_fmac_f32_e32 v9, v4, v20
	v_mul_f32_e32 v10, v7, v23
	v_fmac_f32_e32 v5, v4, v24
	v_mul_f32_e32 v4, v7, v27
	v_fmac_f32_e32 v10, v6, v22
	v_fmac_f32_e32 v4, v6, v26
	v_add_f32_e32 v8, v32, v8
	v_add_f32_e32 v9, v9, v10
	v_add_f32_e32 v4, v5, v4
	v_add_f32_e32 v95, v35, v9
	v_add_f32_e32 v96, v8, v4
	v_or_b32_e32 v4, v62, v69
	v_ashrrev_i32_e32 v5, 31, v4
	v_lshlrev_b64 v[4:5], 10, v[4:5]
	v_lshl_add_u64 v[4:5], s[56:57], 0, v[4:5]
	v_lshl_add_u64 v[16:17], v[4:5], 0, v[54:55]
	global_load_dwordx4 v[98:101], v[16:17], off nt
	global_load_dwordx4 v[102:105], v[16:17], off offset:16 nt
	global_load_dwordx4 v[106:109], v[16:17], off offset:48 nt
	global_load_dwordx4 v[110:113], v[16:17], off offset:32 nt
	global_load_dwordx4 v[36:39], v[16:17], off offset:112 nt
	global_load_dwordx4 v[40:43], v[16:17], off offset:96 nt
	global_load_dwordx4 v[44:47], v[16:17], off offset:80 nt
	global_load_dwordx4 v[48:51], v[16:17], off offset:64 nt
	global_load_dwordx4 v[20:23], v[16:17], off offset:176 nt
	global_load_dwordx4 v[24:27], v[16:17], off offset:160 nt
	global_load_dwordx4 v[28:31], v[16:17], off offset:144 nt
	global_load_dwordx4 v[32:35], v[16:17], off offset:128 nt
	global_load_dwordx4 v[4:7], v[16:17], off offset:240 nt
	global_load_dwordx4 v[8:11], v[16:17], off offset:224 nt
	global_load_dwordx4 v[12:15], v[16:17], off offset:208 nt
	s_nop 0
	global_load_dwordx4 v[16:19], v[16:17], off offset:192 nt
	v_fma_f32 v93, -v89, v68, v93
	v_fma_f32 v114, -v92, v68, v96
	v_cndmask_b32_e64 v96, v93, v76, s[4:5]
	v_cndmask_b32_e64 v93, v114, v76, s[4:5]
	ds_read_b128 v[114:117], v66
	ds_read_b128 v[118:121], v66 offset:16
	ds_read_b128 v[122:125], v66 offset:256
	ds_read_b128 v[126:129], v66 offset:768
	ds_read_b128 v[130:133], v66 offset:784
	ds_read_b128 v[134:137], v66 offset:512
	ds_read_b128 v[138:141], v66 offset:528
	ds_read_b128 v[142:145], v66 offset:272
	v_fma_f32 v94, -v90, v68, v94
	v_fma_f32 v97, -v91, v68, v95
	v_cndmask_b32_e64 v95, v94, v76, s[4:5]
	v_cndmask_b32_e64 v94, v97, v76, s[4:5]
	s_waitcnt vmcnt(15) lgkmcnt(7)
	v_mul_f32_e32 v97, v99, v115
	v_mul_f32_e32 v115, v101, v117
	s_waitcnt lgkmcnt(5)
	v_mul_f32_e32 v117, v99, v123
	v_mul_f32_e32 v123, v101, v125
	s_waitcnt lgkmcnt(2)
	v_mul_f32_e32 v125, v99, v135
	v_mul_f32_e32 v135, v101, v137
	v_mul_f32_e32 v99, v99, v127
	v_mul_f32_e32 v101, v101, v129
	s_waitcnt vmcnt(14)
	v_mul_f32_e32 v119, v103, v119
	v_mul_f32_e32 v121, v105, v121
	s_waitcnt lgkmcnt(0)
	v_mul_f32_e32 v127, v103, v143
	v_mul_f32_e32 v129, v105, v145
	v_mul_f32_e32 v137, v103, v139
	v_mul_f32_e32 v139, v105, v141
	v_mul_f32_e32 v103, v103, v131
	v_mul_f32_e32 v105, v105, v133
	v_fmac_f32_e32 v97, v98, v114
	v_fmac_f32_e32 v115, v100, v116
	v_fmac_f32_e32 v117, v98, v122
	v_fmac_f32_e32 v123, v100, v124
	v_fmac_f32_e32 v125, v98, v134
	v_fmac_f32_e32 v135, v100, v136
	v_fmac_f32_e32 v99, v98, v126
	v_fmac_f32_e32 v101, v100, v128
	v_fmac_f32_e32 v119, v102, v118
	v_fmac_f32_e32 v121, v104, v120
	v_fmac_f32_e32 v127, v102, v142
	v_fmac_f32_e32 v129, v104, v144
	v_fmac_f32_e32 v137, v102, v138
	v_fmac_f32_e32 v139, v104, v140
	v_fmac_f32_e32 v103, v102, v130
	v_fmac_f32_e32 v105, v104, v132
	v_add_f32_e32 v97, v97, v115
	v_add_f32_e32 v98, v117, v123
	v_add_f32_e32 v100, v125, v135
	v_add_f32_e32 v99, v99, v101
	v_add_f32_e32 v101, v119, v121
	v_add_f32_e32 v102, v127, v129
	v_add_f32_e32 v104, v137, v139
	v_add_f32_e32 v103, v103, v105
	v_add_f32_e32 v97, 0, v97
	v_add_f32_e32 v98, 0, v98
	v_add_f32_e32 v100, 0, v100
	v_add_f32_e32 v99, 0, v99
	v_add_f32_e32 v97, v97, v101
	v_add_f32_e32 v122, v98, v102
	v_add_f32_e32 v126, v100, v104
	v_add_f32_e32 v127, v99, v103
	ds_read_b128 v[98:101], v66 offset:32
	ds_read_b128 v[102:105], v66 offset:48
	ds_read_b128 v[114:117], v66 offset:288
	ds_read_b128 v[118:121], v66 offset:544
	s_waitcnt vmcnt(12) lgkmcnt(3)
	v_mul_f32_e32 v99, v111, v99
	v_mul_f32_e32 v101, v113, v101
	v_fmac_f32_e32 v99, v110, v98
	v_fmac_f32_e32 v101, v112, v100
	v_add_f32_e32 v98, v99, v101
	v_add_f32_e32 v97, v97, v98
	ds_read_b128 v[98:101], v66 offset:304
	s_waitcnt lgkmcnt(2)
	v_mul_f32_e32 v115, v111, v115
	v_fmac_f32_e32 v115, v110, v114
	v_mul_f32_e32 v114, v113, v117
	v_fmac_f32_e32 v114, v112, v116
	v_add_f32_e32 v114, v115, v114
	v_add_f32_e32 v128, v122, v114
	ds_read_b128 v[114:117], v66 offset:560
	ds_read_b128 v[122:125], v66 offset:800
	s_waitcnt lgkmcnt(3)
	v_mul_f32_e32 v119, v111, v119
	v_fmac_f32_e32 v119, v110, v118
	v_mul_f32_e32 v118, v113, v121
	v_fmac_f32_e32 v118, v112, v120
	s_waitcnt lgkmcnt(2)
	v_mul_f32_e32 v99, v107, v99
	v_add_f32_e32 v118, v119, v118
	v_fmac_f32_e32 v99, v106, v98
	v_mul_f32_e32 v98, v109, v101
	v_add_f32_e32 v126, v126, v118
	ds_read_b128 v[118:121], v66 offset:816
	v_fmac_f32_e32 v98, v108, v100
	s_waitcnt lgkmcnt(1)
	v_mul_f32_e32 v111, v111, v123
	v_add_f32_e32 v98, v99, v98
	v_fmac_f32_e32 v111, v110, v122
	v_add_f32_e32 v122, v128, v98
	v_mul_f32_e32 v98, v107, v115
	v_mul_f32_e32 v99, v109, v117
	v_fmac_f32_e32 v98, v106, v114
	v_fmac_f32_e32 v99, v108, v116
	v_mul_f32_e32 v110, v113, v125
	v_mul_f32_e32 v103, v107, v103
	v_add_f32_e32 v98, v98, v99
	v_fmac_f32_e32 v110, v112, v124
	v_fmac_f32_e32 v103, v106, v102
	v_mul_f32_e32 v102, v109, v105
	v_add_f32_e32 v123, v126, v98
	s_waitcnt lgkmcnt(0)
	v_mul_f32_e32 v98, v107, v119
	v_mul_f32_e32 v99, v109, v121
	v_add_f32_e32 v110, v111, v110
	v_fmac_f32_e32 v102, v108, v104
	v_fmac_f32_e32 v98, v106, v118
	v_fmac_f32_e32 v99, v108, v120
	v_add_f32_e32 v110, v127, v110
	v_add_f32_e32 v102, v103, v102
	v_add_f32_e32 v98, v98, v99
	v_add_f32_e32 v97, v97, v102
	v_add_f32_e32 v118, v110, v98
	ds_read_b128 v[98:101], v66 offset:64
	ds_read_b128 v[102:105], v66 offset:80
	ds_read_b128 v[106:109], v66 offset:320
	ds_read_b128 v[110:113], v66 offset:576
	ds_read_b128 v[114:117], v66 offset:832
	s_waitcnt vmcnt(8) lgkmcnt(4)
	v_mul_f32_e32 v99, v49, v99
	v_mul_f32_e32 v101, v51, v101
	s_waitcnt lgkmcnt(2)
	v_mul_f32_e32 v107, v49, v107
	v_fmac_f32_e32 v107, v48, v106
	v_mul_f32_e32 v106, v51, v109
	v_fmac_f32_e32 v99, v48, v98
	v_fmac_f32_e32 v101, v50, v100
	v_fmac_f32_e32 v106, v50, v108
	v_add_f32_e32 v98, v99, v101
	v_add_f32_e32 v106, v107, v106
	v_add_f32_e32 v97, v97, v98
	ds_read_b128 v[98:101], v66 offset:336
	v_add_f32_e32 v119, v122, v106
	ds_read_b128 v[106:109], v66 offset:592
	s_waitcnt lgkmcnt(3)
	v_mul_f32_e32 v111, v49, v111
	s_waitcnt lgkmcnt(2)
	v_mul_f32_e32 v49, v49, v115
	v_fmac_f32_e32 v111, v48, v110
	v_mul_f32_e32 v110, v51, v113
	v_fmac_f32_e32 v49, v48, v114
	v_mul_f32_e32 v48, v51, v117
	v_fmac_f32_e32 v110, v50, v112
	v_fmac_f32_e32 v48, v50, v116
	v_add_f32_e32 v110, v111, v110
	v_add_f32_e32 v48, v49, v48
	v_mul_f32_e32 v49, v45, v103
	v_mul_f32_e32 v50, v47, v105
	v_add_f32_e32 v120, v123, v110
	ds_read_b128 v[110:113], v66 offset:848
	v_fmac_f32_e32 v49, v44, v102
	v_fmac_f32_e32 v50, v46, v104
	v_add_f32_e32 v49, v49, v50
	v_add_f32_e32 v97, v97, v49
	s_waitcnt lgkmcnt(2)
	v_mul_f32_e32 v49, v45, v99
	v_mul_f32_e32 v50, v47, v101
	v_fmac_f32_e32 v49, v44, v98
	v_fmac_f32_e32 v50, v46, v100
	v_add_f32_e32 v49, v49, v50
	v_add_f32_e32 v114, v119, v49
	s_waitcnt lgkmcnt(1)
	v_mul_f32_e32 v49, v45, v107
	s_waitcnt lgkmcnt(0)
	v_mul_f32_e32 v45, v45, v111
	v_fmac_f32_e32 v49, v44, v106
	v_mul_f32_e32 v50, v47, v109
	v_fmac_f32_e32 v45, v44, v110
	v_mul_f32_e32 v44, v47, v113
	v_fmac_f32_e32 v50, v46, v108
	v_fmac_f32_e32 v44, v46, v112
	v_add_f32_e32 v48, v118, v48
	v_add_f32_e32 v49, v49, v50
	v_add_f32_e32 v44, v45, v44
	v_add_f32_e32 v115, v120, v49
	v_add_f32_e32 v110, v48, v44
	ds_read_b128 v[44:47], v66 offset:96
	ds_read_b128 v[48:51], v66 offset:112
	ds_read_b128 v[98:101], v66 offset:352
	ds_read_b128 v[102:105], v66 offset:608
	ds_read_b128 v[106:109], v66 offset:864
	s_waitcnt lgkmcnt(4)
	v_mul_f32_e32 v45, v41, v45
	v_mul_f32_e32 v47, v43, v47
	s_waitcnt lgkmcnt(2)
	v_mul_f32_e32 v99, v41, v99
	v_fmac_f32_e32 v99, v40, v98
	v_mul_f32_e32 v98, v43, v101
	v_fmac_f32_e32 v45, v40, v44
	v_fmac_f32_e32 v47, v42, v46
	v_fmac_f32_e32 v98, v42, v100
	v_add_f32_e32 v44, v45, v47
	v_add_f32_e32 v98, v99, v98
	v_add_f32_e32 v97, v97, v44
	ds_read_b128 v[44:47], v66 offset:368
	v_add_f32_e32 v111, v114, v98
	ds_read_b128 v[98:101], v66 offset:624
	s_waitcnt lgkmcnt(3)
	v_mul_f32_e32 v103, v41, v103
	s_waitcnt lgkmcnt(2)
	v_mul_f32_e32 v41, v41, v107
	v_fmac_f32_e32 v103, v40, v102
	v_mul_f32_e32 v102, v43, v105
	v_fmac_f32_e32 v41, v40, v106
	v_mul_f32_e32 v40, v43, v109
	v_fmac_f32_e32 v102, v42, v104
	v_fmac_f32_e32 v40, v42, v108
	v_add_f32_e32 v102, v103, v102
	v_add_f32_e32 v40, v41, v40
	v_mul_f32_e32 v41, v37, v49
	v_mul_f32_e32 v42, v39, v51
	v_add_f32_e32 v112, v115, v102
	ds_read_b128 v[102:105], v66 offset:880
	v_fmac_f32_e32 v41, v36, v48
	v_fmac_f32_e32 v42, v38, v50
	v_add_f32_e32 v41, v41, v42
	v_add_f32_e32 v48, v97, v41
	s_waitcnt lgkmcnt(2)
	v_mul_f32_e32 v41, v37, v45
	v_mul_f32_e32 v42, v39, v47
	v_fmac_f32_e32 v41, v36, v44
	v_fmac_f32_e32 v42, v38, v46
	v_add_f32_e32 v41, v41, v42
	v_add_f32_e32 v97, v111, v41
	s_waitcnt lgkmcnt(1)
	v_mul_f32_e32 v41, v37, v99
	s_waitcnt lgkmcnt(0)
	v_mul_f32_e32 v37, v37, v103
	v_fmac_f32_e32 v41, v36, v98
	v_mul_f32_e32 v42, v39, v101
	v_fmac_f32_e32 v37, v36, v102
	v_mul_f32_e32 v36, v39, v105
	v_fmac_f32_e32 v42, v38, v100
	v_fmac_f32_e32 v36, v38, v104
	v_add_f32_e32 v40, v110, v40
	v_add_f32_e32 v41, v41, v42
	v_add_f32_e32 v36, v37, v36
	v_add_f32_e32 v106, v112, v41
	v_add_f32_e32 v102, v40, v36
	ds_read_b128 v[36:39], v66 offset:128
	ds_read_b128 v[40:43], v66 offset:144
	ds_read_b128 v[44:47], v66 offset:384
	ds_read_b128 v[98:101], v66 offset:896
	s_waitcnt vmcnt(4) lgkmcnt(3)
	v_mul_f32_e32 v37, v33, v37
	v_mul_f32_e32 v39, v35, v39
	s_waitcnt lgkmcnt(1)
	v_mul_f32_e32 v45, v33, v45
	v_fmac_f32_e32 v45, v32, v44
	v_mul_f32_e32 v44, v35, v47
	v_fmac_f32_e32 v37, v32, v36
	v_fmac_f32_e32 v39, v34, v38
	v_fmac_f32_e32 v44, v34, v46
	v_add_f32_e32 v36, v37, v39
	v_add_f32_e32 v44, v45, v44
	v_add_f32_e32 v103, v48, v36
	ds_read_b128 v[36:39], v66 offset:400
	ds_read_b128 v[48:51], v66 offset:640
	v_add_f32_e32 v97, v97, v44
	ds_read_b128 v[44:47], v66 offset:656
	s_waitcnt lgkmcnt(1)
	v_mul_f32_e32 v49, v33, v49
	v_mul_f32_e32 v33, v33, v99
	v_fmac_f32_e32 v49, v32, v48
	v_mul_f32_e32 v48, v35, v51
	v_fmac_f32_e32 v33, v32, v98
	v_mul_f32_e32 v32, v35, v101
	v_fmac_f32_e32 v48, v34, v50
	v_fmac_f32_e32 v32, v34, v100
	v_add_f32_e32 v48, v49, v48
	v_add_f32_e32 v32, v33, v32
	v_mul_f32_e32 v33, v29, v41
	v_mul_f32_e32 v34, v31, v43
	v_add_f32_e32 v104, v106, v48
	ds_read_b128 v[48:51], v66 offset:912
	v_fmac_f32_e32 v33, v28, v40
	v_fmac_f32_e32 v34, v30, v42
	v_add_f32_e32 v33, v33, v34
	v_add_f32_e32 v40, v103, v33
	v_mul_f32_e32 v33, v29, v37
	v_mul_f32_e32 v34, v31, v39
	v_fmac_f32_e32 v33, v28, v36
	v_fmac_f32_e32 v34, v30, v38
	v_add_f32_e32 v33, v33, v34
	v_add_f32_e32 v97, v97, v33
	s_waitcnt lgkmcnt(1)
	v_mul_f32_e32 v33, v29, v45
	s_waitcnt lgkmcnt(0)
	v_mul_f32_e32 v29, v29, v49
	v_fmac_f32_e32 v33, v28, v44
	v_mul_f32_e32 v34, v31, v47
	v_fmac_f32_e32 v29, v28, v48
	v_mul_f32_e32 v28, v31, v51
	v_fmac_f32_e32 v34, v30, v46
	v_fmac_f32_e32 v28, v30, v50
	v_add_f32_e32 v32, v102, v32
	v_add_f32_e32 v33, v33, v34
	v_add_f32_e32 v28, v29, v28
	v_add_f32_e32 v98, v104, v33
	v_add_f32_e32 v48, v32, v28
	ds_read_b128 v[28:31], v66 offset:160
	ds_read_b128 v[32:35], v66 offset:176
	ds_read_b128 v[36:39], v66 offset:416
	ds_read_b128 v[44:47], v66 offset:928
	s_waitcnt lgkmcnt(3)
	v_mul_f32_e32 v29, v25, v29
	v_mul_f32_e32 v31, v27, v31
	s_waitcnt lgkmcnt(1)
	v_mul_f32_e32 v37, v25, v37
	v_fmac_f32_e32 v37, v24, v36
	v_mul_f32_e32 v36, v27, v39
	v_fmac_f32_e32 v29, v24, v28
	v_fmac_f32_e32 v31, v26, v30
	v_fmac_f32_e32 v36, v26, v38
	v_add_f32_e32 v28, v29, v31
	v_add_f32_e32 v36, v37, v36
	v_add_f32_e32 v49, v40, v28
	ds_read_b128 v[28:31], v66 offset:432
	ds_read_b128 v[40:43], v66 offset:672
	v_add_f32_e32 v50, v97, v36
	ds_read_b128 v[36:39], v66 offset:688
	s_waitcnt lgkmcnt(1)
	v_mul_f32_e32 v41, v25, v41
	v_mul_f32_e32 v25, v25, v45
	v_fmac_f32_e32 v41, v24, v40
	v_mul_f32_e32 v40, v27, v43
	v_fmac_f32_e32 v25, v24, v44
	v_mul_f32_e32 v24, v27, v47
	v_fmac_f32_e32 v40, v26, v42
	v_fmac_f32_e32 v24, v26, v46
	v_add_f32_e32 v40, v41, v40
	v_add_f32_e32 v24, v25, v24
	v_mul_f32_e32 v25, v21, v33
	v_mul_f32_e32 v26, v23, v35
	v_add_f32_e32 v51, v98, v40
	ds_read_b128 v[40:43], v66 offset:944
	v_fmac_f32_e32 v25, v20, v32
	v_fmac_f32_e32 v26, v22, v34
	v_add_f32_e32 v25, v25, v26
	v_add_f32_e32 v32, v49, v25
	v_mul_f32_e32 v25, v21, v29
	v_mul_f32_e32 v26, v23, v31
	v_fmac_f32_e32 v25, v20, v28
	v_fmac_f32_e32 v26, v22, v30
	v_add_f32_e32 v25, v25, v26
	v_add_f32_e32 v44, v50, v25
	s_waitcnt lgkmcnt(1)
	v_mul_f32_e32 v25, v21, v37
	s_waitcnt lgkmcnt(0)
	v_mul_f32_e32 v21, v21, v41
	v_fmac_f32_e32 v25, v20, v36
	v_mul_f32_e32 v26, v23, v39
	v_fmac_f32_e32 v21, v20, v40
	v_mul_f32_e32 v20, v23, v43
	v_fmac_f32_e32 v26, v22, v38
	v_fmac_f32_e32 v20, v22, v42
	v_add_f32_e32 v24, v48, v24
	v_add_f32_e32 v25, v25, v26
	v_add_f32_e32 v20, v21, v20
	v_add_f32_e32 v45, v51, v25
	v_add_f32_e32 v40, v24, v20
	ds_read_b128 v[20:23], v66 offset:192
	ds_read_b128 v[24:27], v66 offset:208
	ds_read_b128 v[28:31], v66 offset:448
	ds_read_b128 v[36:39], v66 offset:960
	s_waitcnt vmcnt(0) lgkmcnt(3)
	v_mul_f32_e32 v21, v17, v21
	v_mul_f32_e32 v23, v19, v23
	s_waitcnt lgkmcnt(1)
	v_mul_f32_e32 v29, v17, v29
	v_fmac_f32_e32 v29, v16, v28
	v_mul_f32_e32 v28, v19, v31
	v_fmac_f32_e32 v21, v16, v20
	v_fmac_f32_e32 v23, v18, v22
	v_fmac_f32_e32 v28, v18, v30
	v_add_f32_e32 v20, v21, v23
	v_add_f32_e32 v28, v29, v28
	v_add_f32_e32 v41, v32, v20
	ds_read_b128 v[20:23], v66 offset:464
	ds_read_b128 v[32:35], v66 offset:704
	v_add_f32_e32 v42, v44, v28
	ds_read_b128 v[28:31], v66 offset:720
	s_waitcnt lgkmcnt(1)
	v_mul_f32_e32 v33, v17, v33
	v_mul_f32_e32 v17, v17, v37
	v_fmac_f32_e32 v33, v16, v32
	v_mul_f32_e32 v32, v19, v35
	v_fmac_f32_e32 v17, v16, v36
	v_mul_f32_e32 v16, v19, v39
	v_fmac_f32_e32 v32, v18, v34
	v_fmac_f32_e32 v16, v18, v38
	v_add_f32_e32 v32, v33, v32
	v_add_f32_e32 v16, v17, v16
	v_mul_f32_e32 v17, v13, v25
	v_mul_f32_e32 v18, v15, v27
	v_add_f32_e32 v43, v45, v32
	ds_read_b128 v[32:35], v66 offset:976
	v_fmac_f32_e32 v17, v12, v24
	v_fmac_f32_e32 v18, v14, v26
	v_add_f32_e32 v17, v17, v18
	v_add_f32_e32 v24, v41, v17
	v_mul_f32_e32 v17, v13, v21
	v_mul_f32_e32 v18, v15, v23
	v_fmac_f32_e32 v17, v12, v20
	v_fmac_f32_e32 v18, v14, v22
	v_add_f32_e32 v17, v17, v18
	v_add_f32_e32 v36, v42, v17
	s_waitcnt lgkmcnt(1)
	v_mul_f32_e32 v17, v13, v29
	s_waitcnt lgkmcnt(0)
	v_mul_f32_e32 v13, v13, v33
	v_fmac_f32_e32 v17, v12, v28
	v_mul_f32_e32 v18, v15, v31
	v_fmac_f32_e32 v13, v12, v32
	v_mul_f32_e32 v12, v15, v35
	v_fmac_f32_e32 v18, v14, v30
	v_fmac_f32_e32 v12, v14, v34
	v_add_f32_e32 v16, v40, v16
	v_add_f32_e32 v17, v17, v18
	v_add_f32_e32 v12, v13, v12
	v_add_f32_e32 v37, v43, v17
	v_add_f32_e32 v32, v16, v12
	ds_read_b128 v[12:15], v66 offset:224
	ds_read_b128 v[16:19], v66 offset:240
	ds_read_b128 v[20:23], v66 offset:480
	ds_read_b128 v[28:31], v66 offset:992
	s_waitcnt lgkmcnt(3)
	v_mul_f32_e32 v13, v9, v13
	v_mul_f32_e32 v15, v11, v15
	v_fmac_f32_e32 v13, v8, v12
	v_fmac_f32_e32 v15, v10, v14
	s_waitcnt lgkmcnt(1)
	v_mul_f32_e32 v21, v9, v21
	v_add_f32_e32 v12, v13, v15
	v_fmac_f32_e32 v21, v8, v20
	v_mul_f32_e32 v20, v11, v23
	v_add_f32_e32 v33, v24, v12
	ds_read_b128 v[12:15], v66 offset:496
	ds_read_b128 v[24:27], v66 offset:736
	v_fmac_f32_e32 v20, v10, v22
	v_add_f32_e32 v20, v21, v20
	v_add_f32_e32 v34, v36, v20
	ds_read_b128 v[20:23], v66 offset:752
	s_waitcnt lgkmcnt(1)
	v_mul_f32_e32 v25, v9, v25
	v_fmac_f32_e32 v25, v8, v24
	v_mul_f32_e32 v24, v11, v27
	v_fmac_f32_e32 v24, v10, v26
	v_mul_f32_e32 v9, v9, v29
	v_add_f32_e32 v24, v25, v24
	v_fmac_f32_e32 v9, v8, v28
	v_mul_f32_e32 v8, v11, v31
	v_add_f32_e32 v35, v37, v24
	ds_read_b128 v[24:27], v66 offset:1008
	v_fmac_f32_e32 v8, v10, v30
	v_add_f32_e32 v8, v9, v8
	v_mul_f32_e32 v9, v5, v17
	v_mul_f32_e32 v10, v7, v19
	v_fmac_f32_e32 v9, v4, v16
	v_fmac_f32_e32 v10, v6, v18
	v_add_f32_e32 v9, v9, v10
	v_mul_f32_e32 v10, v5, v13
	v_mul_f32_e32 v11, v7, v15
	v_fmac_f32_e32 v10, v4, v12
	v_fmac_f32_e32 v11, v6, v14
	v_add_f32_e32 v10, v10, v11
	s_waitcnt lgkmcnt(1)
	v_mul_f32_e32 v11, v5, v21
	s_waitcnt lgkmcnt(0)
	v_mul_f32_e32 v5, v5, v25
	v_fmac_f32_e32 v11, v4, v20
	v_mul_f32_e32 v12, v7, v23
	v_fmac_f32_e32 v5, v4, v24
	v_mul_f32_e32 v4, v7, v27
	v_fmac_f32_e32 v12, v6, v22
	v_fmac_f32_e32 v4, v6, v26
	v_add_f32_e32 v8, v32, v8
	v_add_f32_e32 v11, v11, v12
	v_add_f32_e32 v4, v5, v4
	v_add_f32_e32 v9, v33, v9
	v_add_f32_e32 v10, v34, v10
	v_add_f32_e32 v11, v35, v11
	v_add_f32_e32 v8, v8, v4
	v_lshlrev_b64 v[4:5], 8, v[64:65]
	v_lshl_or_b32 v4, v63, 6, v4
	v_or_b32_e32 v4, v4, v52
	v_lshlrev_b64 v[4:5], 1, v[4:5]
	v_lshl_add_u64 v[6:7], s[16:17], 0, v[4:5]
	flat_load_ushort v12, v[6:7]
	v_lshl_add_u64 v[4:5], s[34:35], 0, v[4:5]
	flat_load_ushort v20, v[4:5]
	v_cmp_lt_i32_e32 vcc, v79, v78
	v_fma_f32 v9, -v89, v70, v9
	v_fma_f32 v10, -v90, v70, v10
	v_cndmask_b32_e32 v6, v77, v79, vcc
	v_cmp_lt_i32_e32 vcc, v80, v78
	v_lshlrev_b32_e32 v19, 2, v6
	v_max_f32_e32 v6, v96, v9
	v_cndmask_b32_e32 v7, v77, v80, vcc
	v_max_f32_e32 v4, v95, v10
	v_lshlrev_b32_e32 v22, 2, v7
	ds_bpermute_b32 v5, v19, v6
	ds_bpermute_b32 v7, v19, v4
	v_cmp_lt_i32_e32 vcc, v81, v78
	v_max_f32_e32 v17, v0, v0
	v_fma_f32 v11, -v91, v70, v11
	s_waitcnt lgkmcnt(0)
	v_max_f32_e32 v5, v5, v5
	v_max_f32_e32 v7, v7, v7
	v_max_f32_e32 v5, v6, v5
	v_max_f32_e32 v4, v4, v7
	ds_bpermute_b32 v6, v22, v5
	ds_bpermute_b32 v7, v22, v4
	v_cndmask_b32_e32 v13, v77, v81, vcc
	v_lshlrev_b32_e32 v13, 2, v13
	v_cmp_lt_i32_e32 vcc, v82, v78
	s_waitcnt lgkmcnt(0)
	v_max_f32_e32 v6, v6, v6
	v_max_f32_e32 v7, v7, v7
	v_max_f32_e32 v5, v5, v6
	v_max_f32_e32 v4, v4, v7
	ds_bpermute_b32 v6, v13, v5
	ds_bpermute_b32 v7, v13, v4
	v_cndmask_b32_e32 v14, v77, v82, vcc
	v_lshlrev_b32_e32 v14, 2, v14
	v_cmp_lt_i32_e32 vcc, v83, v78
	s_waitcnt lgkmcnt(0)
	v_max_f32_e32 v6, v6, v6
	v_max_f32_e32 v7, v7, v7
	v_max_f32_e32 v5, v5, v6
	v_max_f32_e32 v4, v4, v7
	ds_bpermute_b32 v6, v14, v5
	ds_bpermute_b32 v7, v14, v4
	v_cndmask_b32_e32 v15, v77, v83, vcc
	v_lshlrev_b32_e32 v15, 2, v15
	v_cmp_lt_i32_e32 vcc, v84, v78
	s_waitcnt lgkmcnt(0)
	v_max_f32_e32 v6, v6, v6
	v_max_f32_e32 v7, v7, v7
	v_max_f32_e32 v23, v5, v6
	v_max_f32_e32 v24, v4, v7
	ds_read2st64_b32 v[4:5], v71 offset1:1
	ds_read2st64_b32 v[6:7], v71 offset0:2 offset1:3
	ds_bpermute_b32 v25, v15, v23
	ds_bpermute_b32 v26, v15, v24
	v_cndmask_b32_e32 v16, v77, v84, vcc
	v_lshlrev_b32_e32 v32, 2, v16
	v_max_f32_e32 v16, v94, v11
	s_waitcnt lgkmcnt(0)
	v_max_f32_e32 v25, v25, v25
	v_max_f32_e32 v23, v23, v25
	v_max_f32_e32 v26, v26, v26
	v_max_f32_e32 v24, v24, v26
	ds_bpermute_b32 v29, v32, v24
	ds_bpermute_b32 v21, v19, v16
	v_max_f32_e32 v18, v1, v1
	v_fma_f32 v8, -v92, v70, v8
	v_ashrrev_i32_e32 v63, 31, v62
	v_mov_b32_e32 v45, v72
	s_waitcnt lgkmcnt(0)
	v_max_f32_e32 v21, v21, v21
	v_max_f32_e32 v16, v16, v21
	ds_bpermute_b32 v21, v22, v16
	s_mov_b64 s[0:1], 0
	s_waitcnt lgkmcnt(0)
	v_max_f32_e32 v21, v21, v21
	v_max_f32_e32 v16, v16, v21
	ds_bpermute_b32 v21, v13, v16
	s_waitcnt lgkmcnt(0)
	v_max_f32_e32 v21, v21, v21
	s_waitcnt vmcnt(0)
	v_lshlrev_b32_e32 v12, 16, v12
	v_mul_f32_e32 v27, v4, v12
	v_mul_f32_e32 v28, v5, v12
	ds_bpermute_b32 v27, v19, v27
	ds_bpermute_b32 v28, v19, v28
	v_mul_f32_e32 v25, v6, v12
	ds_bpermute_b32 v25, v19, v25
	v_max_f32_e32 v16, v16, v21
	s_waitcnt lgkmcnt(2)
	v_fmac_f32_e32 v27, v4, v12
	s_waitcnt lgkmcnt(1)
	v_fmac_f32_e32 v28, v5, v12
	ds_bpermute_b32 v4, v22, v27
	ds_bpermute_b32 v5, v22, v28
	s_waitcnt lgkmcnt(2)
	v_fmac_f32_e32 v25, v6, v12
	ds_bpermute_b32 v6, v22, v25
	ds_bpermute_b32 v21, v14, v16
	s_waitcnt lgkmcnt(3)
	v_add_f32_e32 v4, v27, v4
	s_waitcnt lgkmcnt(2)
	v_add_f32_e32 v5, v28, v5
	ds_bpermute_b32 v26, v13, v4
	ds_bpermute_b32 v27, v13, v5
	s_waitcnt lgkmcnt(3)
	v_add_f32_e32 v6, v25, v6
	ds_bpermute_b32 v25, v13, v6
	ds_bpermute_b32 v28, v32, v23
	s_waitcnt lgkmcnt(3)
	v_add_f32_e32 v4, v4, v26
	s_waitcnt lgkmcnt(2)
	v_add_f32_e32 v5, v5, v27
	ds_bpermute_b32 v26, v14, v4
	ds_bpermute_b32 v27, v14, v5
	s_waitcnt lgkmcnt(3)
	v_add_f32_e32 v6, v6, v25
	ds_bpermute_b32 v25, v14, v6
	v_max_f32_e32 v21, v21, v21
	s_waitcnt lgkmcnt(2)
	v_add_f32_e32 v26, v4, v26
	s_waitcnt lgkmcnt(1)
	v_add_f32_e32 v5, v5, v27
	ds_bpermute_b32 v27, v15, v26
	v_lshlrev_b32_e32 v4, 16, v20
	s_waitcnt lgkmcnt(1)
	v_add_f32_e32 v6, v6, v25
	ds_bpermute_b32 v25, v15, v5
	ds_bpermute_b32 v30, v15, v6
	s_waitcnt lgkmcnt(2)
	v_add_f32_e32 v20, v26, v27
	ds_bpermute_b32 v26, v32, v20
	v_max_f32_e32 v16, v16, v21
	s_waitcnt lgkmcnt(2)
	v_add_f32_e32 v5, v5, v25
	ds_bpermute_b32 v25, v32, v5
	s_waitcnt lgkmcnt(2)
	v_add_f32_e32 v6, v6, v30
	s_waitcnt lgkmcnt(1)
	v_add_f32_e32 v20, v20, v26
	v_max_f32_e32 v17, v20, v17
	v_max3_f32 v33, v23, v28, v17
	v_sub_f32_e32 v17, v96, v33
	v_sub_f32_e32 v9, v9, v33
	v_mul_f32_e32 v17, 0x3fb8aa3b, v17
	v_mul_f32_e32 v9, 0x3fb8aa3b, v9
	v_exp_f32_e32 v17, v17
	v_exp_f32_e32 v9, v9
	s_waitcnt lgkmcnt(0)
	v_add_f32_e32 v5, v5, v25
	v_max_f32_e32 v18, v5, v18
	v_max3_f32 v34, v24, v29, v18
	v_add_f32_e32 v18, v17, v9
	ds_bpermute_b32 v23, v19, v18
	v_sub_f32_e32 v24, v95, v34
	v_sub_f32_e32 v10, v10, v34
	v_mul_f32_e32 v24, 0x3fb8aa3b, v24
	v_mul_f32_e32 v10, 0x3fb8aa3b, v10
	s_waitcnt lgkmcnt(0)
	v_add_f32_e32 v18, v18, v23
	ds_bpermute_b32 v23, v22, v18
	v_exp_f32_e32 v24, v24
	v_exp_f32_e32 v10, v10
	ds_write2st64_b32 v71, v17, v9 offset0:4 offset1:5
	v_sub_f32_e32 v5, v5, v34
	s_waitcnt lgkmcnt(1)
	v_add_f32_e32 v18, v18, v23
	ds_bpermute_b32 v23, v13, v18
	v_add_f32_e32 v25, v24, v10
	ds_bpermute_b32 v26, v19, v25
	v_mul_f32_e32 v5, 0x3fb8aa3b, v5
	ds_bpermute_b32 v27, v32, v6
	s_waitcnt lgkmcnt(2)
	v_add_f32_e32 v18, v18, v23
	ds_bpermute_b32 v23, v14, v18
	s_waitcnt lgkmcnt(2)
	v_add_f32_e32 v9, v25, v26
	ds_bpermute_b32 v17, v22, v9
	v_max_f32_e32 v25, v93, v8
	v_exp_f32_e32 v21, v5
	s_waitcnt lgkmcnt(1)
	v_add_f32_e32 v35, v18, v23
	ds_bpermute_b32 v18, v15, v16
	v_mul_f32_e32 v23, v7, v12
	s_waitcnt lgkmcnt(1)
	v_add_f32_e32 v5, v9, v17
	ds_bpermute_b32 v23, v19, v23
	ds_bpermute_b32 v26, v19, v25
	s_waitcnt lgkmcnt(2)
	v_max_f32_e32 v17, v18, v18
	v_max_f32_e32 v16, v16, v17
	ds_bpermute_b32 v17, v32, v16
	v_add_f32_e32 v6, v6, v27
	v_max_f32_e32 v18, v2, v2
	s_waitcnt lgkmcnt(2)
	v_fmac_f32_e32 v23, v7, v12
	s_waitcnt lgkmcnt(1)
	v_max_f32_e32 v12, v26, v26
	v_max_f32_e32 v18, v6, v18
	v_max_f32_e32 v12, v25, v12
	s_waitcnt lgkmcnt(0)
	v_max3_f32 v37, v16, v17, v18
	ds_bpermute_b32 v16, v22, v12
	ds_bpermute_b32 v7, v22, v23
	v_sub_f32_e32 v17, v94, v37
	v_sub_f32_e32 v11, v11, v37
	ds_bpermute_b32 v9, v13, v5
	s_waitcnt lgkmcnt(2)
	v_max_f32_e32 v16, v16, v16
	v_max_f32_e32 v12, v12, v16
	s_waitcnt lgkmcnt(1)
	v_add_f32_e32 v7, v23, v7
	ds_bpermute_b32 v16, v13, v12
	ds_bpermute_b32 v18, v13, v7
	v_mul_f32_e32 v17, 0x3fb8aa3b, v17
	v_mul_f32_e32 v11, 0x3fb8aa3b, v11
	v_exp_f32_e32 v17, v17
	s_waitcnt lgkmcnt(1)
	v_max_f32_e32 v16, v16, v16
	s_waitcnt lgkmcnt(0)
	v_add_f32_e32 v7, v7, v18
	v_max_f32_e32 v12, v12, v16
	ds_bpermute_b32 v18, v14, v7
	ds_bpermute_b32 v16, v14, v12
	v_exp_f32_e32 v11, v11
	v_add_f32_e32 v5, v5, v9
	ds_write2st64_b32 v85, v24, v10 offset0:6 offset1:7
	s_waitcnt lgkmcnt(2)
	v_add_f32_e32 v7, v7, v18
	s_waitcnt lgkmcnt(1)
	v_max_f32_e32 v16, v16, v16
	ds_bpermute_b32 v18, v15, v7
	v_max_f32_e32 v12, v12, v16
	ds_bpermute_b32 v16, v15, v12
	v_add_f32_e32 v9, v17, v11
	ds_bpermute_b32 v23, v19, v9
	s_waitcnt lgkmcnt(2)
	v_add_f32_e32 v7, v7, v18
	ds_bpermute_b32 v18, v32, v7
	s_waitcnt lgkmcnt(2)
	v_max_f32_e32 v16, v16, v16
	v_max_f32_e32 v12, v12, v16
	ds_bpermute_b32 v16, v32, v12
	s_waitcnt lgkmcnt(2)
	v_add_f32_e32 v9, v9, v23
	s_waitcnt lgkmcnt(1)
	v_add_f32_e32 v7, v7, v18
	v_max_f32_e32 v18, v3, v3
	v_max_f32_e32 v18, v7, v18
	s_waitcnt lgkmcnt(0)
	v_max3_f32 v38, v12, v16, v18
	v_sub_f32_e32 v12, v93, v38
	v_sub_f32_e32 v8, v8, v38
	v_mul_f32_e32 v12, 0x3fb8aa3b, v12
	v_mul_f32_e32 v8, 0x3fb8aa3b, v8
	v_exp_f32_e32 v12, v12
	v_exp_f32_e32 v8, v8
	ds_bpermute_b32 v16, v14, v5
	ds_bpermute_b32 v18, v22, v9
	v_sub_f32_e32 v6, v6, v37
	v_add_f32_e32 v23, v12, v8
	ds_bpermute_b32 v19, v19, v23
	s_waitcnt lgkmcnt(2)
	v_add_f32_e32 v39, v5, v16
	s_waitcnt lgkmcnt(1)
	v_add_f32_e32 v5, v9, v18
	ds_bpermute_b32 v9, v13, v5
	v_mul_f32_e32 v6, 0x3fb8aa3b, v6
	s_waitcnt lgkmcnt(1)
	v_add_f32_e32 v16, v23, v19
	ds_bpermute_b32 v18, v22, v16
	v_exp_f32_e32 v24, v6
	s_waitcnt lgkmcnt(1)
	v_add_f32_e32 v5, v5, v9
	ds_bpermute_b32 v9, v14, v5
	v_sub_f32_e32 v20, v20, v33
	s_waitcnt lgkmcnt(1)
	v_add_f32_e32 v10, v16, v18
	ds_bpermute_b32 v13, v13, v10
	v_sub_f32_e32 v7, v7, v38
	s_waitcnt lgkmcnt(1)
	v_add_f32_e32 v41, v5, v9
	v_mul_f32_e32 v20, 0x3fb8aa3b, v20
	v_mul_f32_e32 v7, 0x3fb8aa3b, v7
	s_waitcnt lgkmcnt(0)
	v_add_f32_e32 v5, v10, v13
	ds_bpermute_b32 v6, v14, v5
	v_exp_f32_e32 v20, v20
	v_exp_f32_e32 v25, v7
	ds_bpermute_b32 v36, v15, v35
	ds_bpermute_b32 v40, v15, v39
	s_waitcnt lgkmcnt(2)
	v_add_f32_e32 v43, v5, v6
	ds_bpermute_b32 v42, v15, v41
	ds_bpermute_b32 v44, v15, v43
	ds_write2st64_b32 v86, v17, v11 offset0:8 offset1:9
	ds_write2st64_b32 v87, v12, v8 offset0:10 offset1:11
	v_pk_mul_f32 v[26:27], v[24:25], v[4:5] op_sel_hi:[1,0]
	v_pk_mul_f32 v[22:23], v[20:21], v[4:5] op_sel_hi:[1,0]
	s_waitcnt lgkmcnt(0)
	v_lshlrev_b64 v[4:5], 10, v[62:63]
	v_lshl_or_b32 v4, v88, 8, v4
	v_lshl_add_u64 v[28:29], v[56:57], 0, v[4:5]

.LBB0_1394:
	v_lshrrev_b32_e32 v140, 4, v52
	v_and_b32_e32 v141, 15, v52
	v_lshlrev_b32_e32 v140, 10, v140
	v_lshl_add_u32 v140, v141, 4, v140
	v_ashrrev_i32_e32 v141, 2, v53
	v_lshl_add_u32 v140, v141, 17, v140
	v_and_b32_e32 v141, 3, v53
	v_lshl_add_u32 v140, v141, 8, v140
	v_add_u32_e32 v140, 0x1000000, v140
	v_mov_b32_e32 v141, 0
	v_readlane_b32 s0, v254, 20
	v_readlane_b32 s1, v254, 21
	s_nop 1
	v_lshl_add_u64 v[142:143], s[0:1], 0, v[140:141]
	v_mov_b32_e32 v144, 0x1000
	v_mov_b32_e32 v145, 0
	global_load_dwordx4 v[148:151], v[142:143], off
	v_lshl_add_u64 v[142:143], v[142:143], 0, v[144:145]
	global_load_dwordx4 v[148:151], v[142:143], off
	v_lshl_add_u64 v[142:143], v[142:143], 0, v[144:145]
	global_load_dwordx4 v[148:151], v[142:143], off
	v_lshl_add_u64 v[142:143], v[142:143], 0, v[144:145]
	global_load_dwordx4 v[148:151], v[142:143], off
	v_lshl_add_u64 v[142:143], v[142:143], 0, v[144:145]
	global_load_dwordx4 v[148:151], v[142:143], off
	v_lshl_add_u64 v[142:143], v[142:143], 0, v[144:145]
	global_load_dwordx4 v[148:151], v[142:143], off
	v_lshl_add_u64 v[142:143], v[142:143], 0, v[144:145]
	global_load_dwordx4 v[148:151], v[142:143], off
	v_lshl_add_u64 v[142:143], v[142:143], 0, v[144:145]
	global_load_dwordx4 v[148:151], v[142:143], off
	v_lshl_add_u64 v[142:143], v[142:143], 0, v[144:145]
	global_load_dwordx4 v[148:151], v[142:143], off
	v_lshl_add_u64 v[142:143], v[142:143], 0, v[144:145]
	global_load_dwordx4 v[148:151], v[142:143], off
	v_lshl_add_u64 v[142:143], v[142:143], 0, v[144:145]
	global_load_dwordx4 v[148:151], v[142:143], off
	v_lshl_add_u64 v[142:143], v[142:143], 0, v[144:145]
	global_load_dwordx4 v[148:151], v[142:143], off
	v_lshl_add_u64 v[142:143], v[142:143], 0, v[144:145]
	global_load_dwordx4 v[148:151], v[142:143], off
	v_lshl_add_u64 v[142:143], v[142:143], 0, v[144:145]
	global_load_dwordx4 v[148:151], v[142:143], off
	v_lshl_add_u64 v[142:143], v[142:143], 0, v[144:145]
	global_load_dwordx4 v[148:151], v[142:143], off
	v_lshl_add_u64 v[142:143], v[142:143], 0, v[144:145]
	global_load_dwordx4 v[148:151], v[142:143], off
	v_lshl_add_u64 v[142:143], v[142:143], 0, v[144:145]
	global_load_dwordx4 v[148:151], v[142:143], off
	v_lshl_add_u64 v[142:143], v[142:143], 0, v[144:145]
	global_load_dwordx4 v[148:151], v[142:143], off
	v_lshl_add_u64 v[142:143], v[142:143], 0, v[144:145]
	global_load_dwordx4 v[148:151], v[142:143], off
	v_lshl_add_u64 v[142:143], v[142:143], 0, v[144:145]
	global_load_dwordx4 v[148:151], v[142:143], off
	v_lshl_add_u64 v[142:143], v[142:143], 0, v[144:145]
	global_load_dwordx4 v[148:151], v[142:143], off
	v_lshl_add_u64 v[142:143], v[142:143], 0, v[144:145]
	global_load_dwordx4 v[148:151], v[142:143], off
	v_lshl_add_u64 v[142:143], v[142:143], 0, v[144:145]
	global_load_dwordx4 v[148:151], v[142:143], off
	v_lshl_add_u64 v[142:143], v[142:143], 0, v[144:145]
	global_load_dwordx4 v[148:151], v[142:143], off
	v_lshl_add_u64 v[142:143], v[142:143], 0, v[144:145]
	global_load_dwordx4 v[148:151], v[142:143], off
	v_lshl_add_u64 v[142:143], v[142:143], 0, v[144:145]
	global_load_dwordx4 v[148:151], v[142:143], off
	v_lshl_add_u64 v[142:143], v[142:143], 0, v[144:145]
	global_load_dwordx4 v[148:151], v[142:143], off
	v_lshl_add_u64 v[142:143], v[142:143], 0, v[144:145]
	global_load_dwordx4 v[148:151], v[142:143], off
	v_lshl_add_u64 v[142:143], v[142:143], 0, v[144:145]
	global_load_dwordx4 v[148:151], v[142:143], off
	v_lshl_add_u64 v[142:143], v[142:143], 0, v[144:145]
	global_load_dwordx4 v[148:151], v[142:143], off
	v_lshl_add_u64 v[142:143], v[142:143], 0, v[144:145]
	global_load_dwordx4 v[148:151], v[142:143], off
	v_lshl_add_u64 v[142:143], v[142:143], 0, v[144:145]
	global_load_dwordx4 v[148:151], v[142:143], off
	v_readlane_b32 s0, v254, 18
	v_readlane_b32 s1, v254, 19
	s_nop 1
	v_lshl_add_u64 v[142:143], s[0:1], 0, v[140:141]
	v_mov_b32_e32 v144, 0x1000
	v_mov_b32_e32 v145, 0
	global_load_dwordx4 v[148:151], v[142:143], off
	v_lshl_add_u64 v[142:143], v[142:143], 0, v[144:145]
	global_load_dwordx4 v[148:151], v[142:143], off
	v_lshl_add_u64 v[142:143], v[142:143], 0, v[144:145]
	global_load_dwordx4 v[148:151], v[142:143], off
	v_lshl_add_u64 v[142:143], v[142:143], 0, v[144:145]
	global_load_dwordx4 v[148:151], v[142:143], off
	v_lshl_add_u64 v[142:143], v[142:143], 0, v[144:145]
	global_load_dwordx4 v[148:151], v[142:143], off
	v_lshl_add_u64 v[142:143], v[142:143], 0, v[144:145]
	global_load_dwordx4 v[148:151], v[142:143], off
	v_lshl_add_u64 v[142:143], v[142:143], 0, v[144:145]
	global_load_dwordx4 v[148:151], v[142:143], off
	v_lshl_add_u64 v[142:143], v[142:143], 0, v[144:145]
	global_load_dwordx4 v[148:151], v[142:143], off
	v_lshl_add_u64 v[142:143], v[142:143], 0, v[144:145]
	global_load_dwordx4 v[148:151], v[142:143], off
	v_lshl_add_u64 v[142:143], v[142:143], 0, v[144:145]
	global_load_dwordx4 v[148:151], v[142:143], off
	v_lshl_add_u64 v[142:143], v[142:143], 0, v[144:145]
	global_load_dwordx4 v[148:151], v[142:143], off
	v_lshl_add_u64 v[142:143], v[142:143], 0, v[144:145]
	global_load_dwordx4 v[148:151], v[142:143], off
	v_lshl_add_u64 v[142:143], v[142:143], 0, v[144:145]
	global_load_dwordx4 v[148:151], v[142:143], off
	v_lshl_add_u64 v[142:143], v[142:143], 0, v[144:145]
	global_load_dwordx4 v[148:151], v[142:143], off
	v_lshl_add_u64 v[142:143], v[142:143], 0, v[144:145]
	global_load_dwordx4 v[148:151], v[142:143], off
	v_lshl_add_u64 v[142:143], v[142:143], 0, v[144:145]
	global_load_dwordx4 v[148:151], v[142:143], off
	v_lshl_add_u64 v[142:143], v[142:143], 0, v[144:145]
	global_load_dwordx4 v[148:151], v[142:143], off
	v_lshl_add_u64 v[142:143], v[142:143], 0, v[144:145]
	global_load_dwordx4 v[148:151], v[142:143], off
	v_lshl_add_u64 v[142:143], v[142:143], 0, v[144:145]
	global_load_dwordx4 v[148:151], v[142:143], off
	v_lshl_add_u64 v[142:143], v[142:143], 0, v[144:145]
	global_load_dwordx4 v[148:151], v[142:143], off
	v_lshl_add_u64 v[142:143], v[142:143], 0, v[144:145]
	global_load_dwordx4 v[148:151], v[142:143], off
	v_lshl_add_u64 v[142:143], v[142:143], 0, v[144:145]
	global_load_dwordx4 v[148:151], v[142:143], off
	v_lshl_add_u64 v[142:143], v[142:143], 0, v[144:145]
	global_load_dwordx4 v[148:151], v[142:143], off
	v_lshl_add_u64 v[142:143], v[142:143], 0, v[144:145]
	global_load_dwordx4 v[148:151], v[142:143], off
	v_lshl_add_u64 v[142:143], v[142:143], 0, v[144:145]
	global_load_dwordx4 v[148:151], v[142:143], off
	v_lshl_add_u64 v[142:143], v[142:143], 0, v[144:145]
	global_load_dwordx4 v[148:151], v[142:143], off
	v_lshl_add_u64 v[142:143], v[142:143], 0, v[144:145]
	global_load_dwordx4 v[148:151], v[142:143], off
	v_lshl_add_u64 v[142:143], v[142:143], 0, v[144:145]
	global_load_dwordx4 v[148:151], v[142:143], off
	v_lshl_add_u64 v[142:143], v[142:143], 0, v[144:145]
	global_load_dwordx4 v[148:151], v[142:143], off
	v_lshl_add_u64 v[142:143], v[142:143], 0, v[144:145]
	global_load_dwordx4 v[148:151], v[142:143], off
	v_lshl_add_u64 v[142:143], v[142:143], 0, v[144:145]
	global_load_dwordx4 v[148:151], v[142:143], off
	v_lshl_add_u64 v[142:143], v[142:143], 0, v[144:145]
	global_load_dwordx4 v[148:151], v[142:143], off
	v_ashrrev_i32_e32 v4, 2, v53
	v_add_u32_e32 v64, 0x2000, v4
	v_ashrrev_i32_e32 v65, 31, v64
	v_and_b32_e32 v63, 3, v53
	v_lshlrev_b64 v[0:1], 11, v[64:65]
	v_lshl_add_u64 v[0:1], s[4:5], 0, v[0:1]
	v_lshlrev_b32_e32 v2, 9, v63
	v_mov_b32_e32 v3, v55
	v_lshl_add_u64 v[0:1], v[0:1], 0, v[2:3]
	v_lshl_add_u64 v[0:1], v[0:1], 0, v[58:59]
	global_load_dwordx2 v[2:3], v[0:1], off
	v_lshlrev_b32_e32 v62, 7, v4
	v_or_b32_e32 v0, v62, v52
	v_ashrrev_i32_e32 v1, 31, v0
	v_lshlrev_b64 v[0:1], 10, v[0:1]
	v_lshlrev_b32_e32 v54, 8, v63
	v_lshl_add_u64 v[0:1], s[30:31], 0, v[0:1]
	v_lshl_add_u64 v[16:17], v[0:1], 0, v[54:55]
	v_readlane_b32 s36, v254, 30
	v_readlane_b32 s40, v254, 34
	v_readlane_b32 s41, v254, 35
	v_lshlrev_b64 v[60:61], 10, v[64:65]
	v_and_b32_e32 v88, 3, v73
	v_readlane_b32 s37, v254, 31
	v_readlane_b32 s38, v254, 32
	v_readlane_b32 s39, v254, 33
	v_readlane_b32 s42, v254, 36
	v_readlane_b32 s43, v254, 37
	v_readlane_b32 s44, v254, 38
	v_readlane_b32 s45, v254, 39
	v_readlane_b32 s46, v254, 40
	v_readlane_b32 s47, v254, 41
	v_readlane_b32 s48, v254, 42
	v_readlane_b32 s49, v254, 43
	v_readlane_b32 s50, v254, 44
	v_readlane_b32 s51, v254, 45
	s_waitcnt vmcnt(0)
	v_lshlrev_b32_e32 v0, 16, v2
	v_and_b32_e32 v1, 0xffff0000, v2
	v_lshlrev_b32_e32 v2, 16, v3
	v_and_b32_e32 v3, 0xffff0000, v3
	ds_write_b128 v67, v[0:3]
	v_lshlrev_b32_e32 v0, 2, v63
	s_waitcnt lgkmcnt(0)
	v_lshlrev_b32_e32 v1, 4, v63
	v_or_b32_e32 v2, 1, v0
	v_or_b32_e32 v3, 2, v0
	v_or_b32_e32 v4, 3, v0
	v_add_u32_e32 v0, 4, v0
	global_load_dwordx4 v[94:97], v[16:17], off nt
	global_load_dwordx4 v[98:101], v[16:17], off offset:16 nt
	v_cvt_f32_ubyte0_e32 v89, v2
	v_cvt_f32_ubyte0_e32 v90, v3
	v_cvt_f32_ubyte0_e32 v91, v4
	v_cvt_f32_ubyte0_e32 v92, v0
	global_load_dwordx4 v[0:3], v1, s[40:41] offset:64
	s_nop 0
	global_load_dwordx4 v[102:105], v[16:17], off offset:48 nt
	global_load_dwordx4 v[106:109], v[16:17], off offset:32 nt
	global_load_dwordx4 v[36:39], v[16:17], off offset:112 nt
	global_load_dwordx4 v[40:43], v[16:17], off offset:96 nt
	global_load_dwordx4 v[44:47], v[16:17], off offset:80 nt
	global_load_dwordx4 v[48:51], v[16:17], off offset:64 nt
	global_load_dwordx4 v[20:23], v[16:17], off offset:176 nt
	global_load_dwordx4 v[24:27], v[16:17], off offset:160 nt
	global_load_dwordx4 v[28:31], v[16:17], off offset:144 nt
	global_load_dwordx4 v[32:35], v[16:17], off offset:128 nt
	global_load_dwordx4 v[4:7], v[16:17], off offset:240 nt
	global_load_dwordx4 v[8:11], v[16:17], off offset:224 nt
	global_load_dwordx4 v[12:15], v[16:17], off offset:208 nt
	s_nop 0
	global_load_dwordx4 v[16:19], v[16:17], off offset:192 nt
	v_mul_f32_e32 v110, -0.5, v90
	v_mul_f32_e32 v111, -0.5, v91
	v_mul_f32_e32 v112, -0.5, v92
	v_cmp_gt_f32_e64 s[0:1], s9, v110
	v_cmp_gt_f32_e64 s[10:11], s9, v111
	v_cmp_gt_f32_e64 s[12:13], s9, v112
	v_cndmask_b32_e64 v110, 0, v74, s[0:1]
	v_cndmask_b32_e64 v111, 0, v74, s[10:11]
	v_cndmask_b32_e64 v112, 0, v74, s[12:13]
	v_fmac_f32_e32 v110, -0.5, v90
	v_fmac_f32_e32 v111, -0.5, v91
	v_fmac_f32_e32 v112, -0.5, v92
	v_mul_f32_e32 v93, -0.5, v89
	v_exp_f32_e32 v110, v110
	v_exp_f32_e32 v111, v111
	v_exp_f32_e32 v112, v112
	v_cmp_gt_f32_e32 vcc, s9, v93
	v_cndmask_b32_e64 v90, 0, v75, s[0:1]
	v_cndmask_b32_e64 v91, 0, v75, s[10:11]
	v_cndmask_b32_e32 v93, 0, v74, vcc
	v_fmac_f32_e32 v93, -0.5, v89
	v_cndmask_b32_e64 v92, 0, v75, s[12:13]
	v_exp_f32_e32 v93, v93
	v_ldexp_f32 v90, v110, v90
	v_ldexp_f32 v91, v111, v91
	v_ldexp_f32 v92, v112, v92
	ds_read_b128 v[110:113], v66
	ds_read_b128 v[114:117], v66 offset:16
	ds_read_b128 v[118:121], v66 offset:256
	ds_read_b128 v[122:125], v66 offset:768
	ds_read_b128 v[126:129], v66 offset:784
	ds_read_b128 v[130:133], v66 offset:512
	ds_read_b128 v[134:137], v66 offset:528
	ds_read_b128 v[138:141], v66 offset:272
	v_cndmask_b32_e32 v89, 0, v75, vcc
	v_ldexp_f32 v89, v93, v89
	s_waitcnt vmcnt(0) lgkmcnt(0)
	v_mul_f32_e32 v93, v95, v111
	v_mul_f32_e32 v111, v97, v113
	s_waitcnt lgkmcnt(5)
	v_mul_f32_e32 v113, v95, v119
	v_mul_f32_e32 v119, v97, v121
	s_waitcnt lgkmcnt(2)
	v_mul_f32_e32 v121, v95, v131
	v_mul_f32_e32 v131, v97, v133
	v_mul_f32_e32 v95, v95, v123
	v_mul_f32_e32 v97, v97, v125
	s_waitcnt vmcnt(15)
	v_mul_f32_e32 v115, v99, v115
	v_mul_f32_e32 v117, v101, v117
	s_waitcnt lgkmcnt(0)
	v_mul_f32_e32 v123, v99, v139
	v_mul_f32_e32 v125, v101, v141
	v_mul_f32_e32 v133, v99, v135
	v_mul_f32_e32 v135, v101, v137
	v_mul_f32_e32 v99, v99, v127
	v_mul_f32_e32 v101, v101, v129
	v_fmac_f32_e32 v93, v94, v110
	v_fmac_f32_e32 v111, v96, v112
	v_fmac_f32_e32 v113, v94, v118
	v_fmac_f32_e32 v119, v96, v120
	v_fmac_f32_e32 v121, v94, v130
	v_fmac_f32_e32 v131, v96, v132
	v_fmac_f32_e32 v95, v94, v122
	v_fmac_f32_e32 v97, v96, v124
	v_fmac_f32_e32 v115, v98, v114
	v_fmac_f32_e32 v117, v100, v116
	v_fmac_f32_e32 v123, v98, v138
	v_fmac_f32_e32 v125, v100, v140
	v_fmac_f32_e32 v133, v98, v134
	v_fmac_f32_e32 v135, v100, v136
	v_fmac_f32_e32 v99, v98, v126
	v_fmac_f32_e32 v101, v100, v128
	v_add_f32_e32 v93, v93, v111
	v_add_f32_e32 v94, v113, v119
	v_add_f32_e32 v96, v121, v131
	v_add_f32_e32 v95, v95, v97
	v_add_f32_e32 v97, v115, v117
	v_add_f32_e32 v98, v123, v125
	v_add_f32_e32 v100, v133, v135
	v_add_f32_e32 v99, v99, v101
	v_add_f32_e32 v93, 0, v93
	v_add_f32_e32 v94, 0, v94
	v_add_f32_e32 v96, 0, v96
	v_add_f32_e32 v95, 0, v95
	v_add_f32_e32 v93, v93, v97
	v_add_f32_e32 v118, v94, v98
	v_add_f32_e32 v122, v96, v100
	v_add_f32_e32 v123, v95, v99
	ds_read_b128 v[94:97], v66 offset:32
	ds_read_b128 v[98:101], v66 offset:48
	ds_read_b128 v[110:113], v66 offset:288
	ds_read_b128 v[114:117], v66 offset:544
	s_waitcnt vmcnt(12) lgkmcnt(3)
	v_mul_f32_e32 v95, v107, v95
	v_mul_f32_e32 v97, v109, v97
	v_fmac_f32_e32 v95, v106, v94
	v_fmac_f32_e32 v97, v108, v96
	v_add_f32_e32 v94, v95, v97
	v_add_f32_e32 v93, v93, v94
	ds_read_b128 v[94:97], v66 offset:304
	s_waitcnt lgkmcnt(2)
	v_mul_f32_e32 v111, v107, v111
	v_fmac_f32_e32 v111, v106, v110
	v_mul_f32_e32 v110, v109, v113
	v_fmac_f32_e32 v110, v108, v112
	v_add_f32_e32 v110, v111, v110
	v_add_f32_e32 v124, v118, v110
	ds_read_b128 v[110:113], v66 offset:560
	ds_read_b128 v[118:121], v66 offset:800
	s_waitcnt lgkmcnt(3)
	v_mul_f32_e32 v115, v107, v115
	v_fmac_f32_e32 v115, v106, v114
	v_mul_f32_e32 v114, v109, v117
	v_fmac_f32_e32 v114, v108, v116
	s_waitcnt lgkmcnt(2)
	v_mul_f32_e32 v95, v103, v95
	v_add_f32_e32 v114, v115, v114
	v_fmac_f32_e32 v95, v102, v94
	v_mul_f32_e32 v94, v105, v97
	v_add_f32_e32 v122, v122, v114
	ds_read_b128 v[114:117], v66 offset:816
	v_fmac_f32_e32 v94, v104, v96
	s_waitcnt lgkmcnt(1)
	v_mul_f32_e32 v107, v107, v119
	v_add_f32_e32 v94, v95, v94
	v_fmac_f32_e32 v107, v106, v118
	v_add_f32_e32 v118, v124, v94
	v_mul_f32_e32 v94, v103, v111
	v_mul_f32_e32 v95, v105, v113
	v_fmac_f32_e32 v94, v102, v110
	v_fmac_f32_e32 v95, v104, v112
	v_mul_f32_e32 v106, v109, v121
	v_mul_f32_e32 v99, v103, v99
	v_add_f32_e32 v94, v94, v95
	v_fmac_f32_e32 v106, v108, v120
	v_fmac_f32_e32 v99, v102, v98
	v_mul_f32_e32 v98, v105, v101
	v_add_f32_e32 v119, v122, v94
	s_waitcnt lgkmcnt(0)
	v_mul_f32_e32 v94, v103, v115
	v_mul_f32_e32 v95, v105, v117
	v_add_f32_e32 v106, v107, v106
	v_fmac_f32_e32 v98, v104, v100
	v_fmac_f32_e32 v94, v102, v114
	v_fmac_f32_e32 v95, v104, v116
	v_add_f32_e32 v106, v123, v106
	v_add_f32_e32 v98, v99, v98
	v_add_f32_e32 v94, v94, v95
	v_add_f32_e32 v93, v93, v98
	v_add_f32_e32 v114, v106, v94
	ds_read_b128 v[94:97], v66 offset:64
	ds_read_b128 v[98:101], v66 offset:80
	ds_read_b128 v[102:105], v66 offset:320
	ds_read_b128 v[106:109], v66 offset:576
	ds_read_b128 v[110:113], v66 offset:832
	s_waitcnt vmcnt(8) lgkmcnt(4)
	v_mul_f32_e32 v95, v49, v95
	v_mul_f32_e32 v97, v51, v97
	s_waitcnt lgkmcnt(2)
	v_mul_f32_e32 v103, v49, v103
	v_fmac_f32_e32 v103, v48, v102
	v_mul_f32_e32 v102, v51, v105
	v_fmac_f32_e32 v95, v48, v94
	v_fmac_f32_e32 v97, v50, v96
	v_fmac_f32_e32 v102, v50, v104
	v_add_f32_e32 v94, v95, v97
	v_add_f32_e32 v102, v103, v102
	v_add_f32_e32 v93, v93, v94
	ds_read_b128 v[94:97], v66 offset:336
	v_add_f32_e32 v115, v118, v102
	ds_read_b128 v[102:105], v66 offset:592
	s_waitcnt lgkmcnt(3)
	v_mul_f32_e32 v107, v49, v107
	s_waitcnt lgkmcnt(2)
	v_mul_f32_e32 v49, v49, v111
	v_fmac_f32_e32 v107, v48, v106
	v_mul_f32_e32 v106, v51, v109
	v_fmac_f32_e32 v49, v48, v110
	v_mul_f32_e32 v48, v51, v113
	v_fmac_f32_e32 v106, v50, v108
	v_fmac_f32_e32 v48, v50, v112
	v_add_f32_e32 v106, v107, v106
	v_add_f32_e32 v48, v49, v48
	v_mul_f32_e32 v49, v45, v99
	v_mul_f32_e32 v50, v47, v101
	v_add_f32_e32 v116, v119, v106
	ds_read_b128 v[106:109], v66 offset:848
	v_fmac_f32_e32 v49, v44, v98
	v_fmac_f32_e32 v50, v46, v100
	v_add_f32_e32 v49, v49, v50
	v_add_f32_e32 v93, v93, v49
	s_waitcnt lgkmcnt(2)
	v_mul_f32_e32 v49, v45, v95
	v_mul_f32_e32 v50, v47, v97
	v_fmac_f32_e32 v49, v44, v94
	v_fmac_f32_e32 v50, v46, v96
	v_add_f32_e32 v49, v49, v50
	v_add_f32_e32 v110, v115, v49
	s_waitcnt lgkmcnt(1)
	v_mul_f32_e32 v49, v45, v103
	s_waitcnt lgkmcnt(0)
	v_mul_f32_e32 v45, v45, v107
	v_fmac_f32_e32 v49, v44, v102
	v_mul_f32_e32 v50, v47, v105
	v_fmac_f32_e32 v45, v44, v106
	v_mul_f32_e32 v44, v47, v109
	v_fmac_f32_e32 v50, v46, v104
	v_fmac_f32_e32 v44, v46, v108
	v_add_f32_e32 v48, v114, v48
	v_add_f32_e32 v49, v49, v50
	v_add_f32_e32 v44, v45, v44
	v_add_f32_e32 v111, v116, v49
	v_add_f32_e32 v106, v48, v44
	ds_read_b128 v[44:47], v66 offset:96
	ds_read_b128 v[48:51], v66 offset:112
	ds_read_b128 v[94:97], v66 offset:352
	ds_read_b128 v[98:101], v66 offset:608
	ds_read_b128 v[102:105], v66 offset:864
	s_waitcnt lgkmcnt(4)
	v_mul_f32_e32 v45, v41, v45
	v_mul_f32_e32 v47, v43, v47
	s_waitcnt lgkmcnt(2)
	v_mul_f32_e32 v95, v41, v95
	v_fmac_f32_e32 v95, v40, v94
	v_mul_f32_e32 v94, v43, v97
	v_fmac_f32_e32 v45, v40, v44
	v_fmac_f32_e32 v47, v42, v46
	v_fmac_f32_e32 v94, v42, v96
	v_add_f32_e32 v44, v45, v47
	v_add_f32_e32 v94, v95, v94
	v_add_f32_e32 v93, v93, v44
	ds_read_b128 v[44:47], v66 offset:368
	v_add_f32_e32 v107, v110, v94
	ds_read_b128 v[94:97], v66 offset:624
	s_waitcnt lgkmcnt(3)
	v_mul_f32_e32 v99, v41, v99
	s_waitcnt lgkmcnt(2)
	v_mul_f32_e32 v41, v41, v103
	v_fmac_f32_e32 v99, v40, v98
	v_mul_f32_e32 v98, v43, v101
	v_fmac_f32_e32 v41, v40, v102
	v_mul_f32_e32 v40, v43, v105
	v_fmac_f32_e32 v98, v42, v100
	v_fmac_f32_e32 v40, v42, v104
	v_add_f32_e32 v98, v99, v98
	v_add_f32_e32 v40, v41, v40
	v_mul_f32_e32 v41, v37, v49
	v_mul_f32_e32 v42, v39, v51
	v_add_f32_e32 v108, v111, v98
	ds_read_b128 v[98:101], v66 offset:880
	v_fmac_f32_e32 v41, v36, v48
	v_fmac_f32_e32 v42, v38, v50
	v_add_f32_e32 v41, v41, v42
	v_add_f32_e32 v48, v93, v41
	s_waitcnt lgkmcnt(2)
	v_mul_f32_e32 v41, v37, v45
	v_mul_f32_e32 v42, v39, v47
	v_fmac_f32_e32 v41, v36, v44
	v_fmac_f32_e32 v42, v38, v46
	v_add_f32_e32 v41, v41, v42
	v_add_f32_e32 v93, v107, v41
	s_waitcnt lgkmcnt(1)
	v_mul_f32_e32 v41, v37, v95
	s_waitcnt lgkmcnt(0)
	v_mul_f32_e32 v37, v37, v99
	v_fmac_f32_e32 v41, v36, v94
	v_mul_f32_e32 v42, v39, v97
	v_fmac_f32_e32 v37, v36, v98
	v_mul_f32_e32 v36, v39, v101
	v_fmac_f32_e32 v42, v38, v96
	v_fmac_f32_e32 v36, v38, v100
	v_add_f32_e32 v40, v106, v40
	v_add_f32_e32 v41, v41, v42
	v_add_f32_e32 v36, v37, v36
	v_add_f32_e32 v102, v108, v41
	v_add_f32_e32 v98, v40, v36
	ds_read_b128 v[36:39], v66 offset:128
	ds_read_b128 v[40:43], v66 offset:144
	ds_read_b128 v[44:47], v66 offset:384
	ds_read_b128 v[94:97], v66 offset:896
	s_waitcnt vmcnt(4) lgkmcnt(3)
	v_mul_f32_e32 v37, v33, v37
	v_mul_f32_e32 v39, v35, v39
	s_waitcnt lgkmcnt(1)
	v_mul_f32_e32 v45, v33, v45
	v_fmac_f32_e32 v45, v32, v44
	v_mul_f32_e32 v44, v35, v47
	v_fmac_f32_e32 v37, v32, v36
	v_fmac_f32_e32 v39, v34, v38
	v_fmac_f32_e32 v44, v34, v46
	v_add_f32_e32 v36, v37, v39
	v_add_f32_e32 v44, v45, v44
	v_add_f32_e32 v99, v48, v36
	ds_read_b128 v[36:39], v66 offset:400
	ds_read_b128 v[48:51], v66 offset:640
	v_add_f32_e32 v93, v93, v44
	ds_read_b128 v[44:47], v66 offset:656
	s_waitcnt lgkmcnt(1)
	v_mul_f32_e32 v49, v33, v49
	v_mul_f32_e32 v33, v33, v95
	v_fmac_f32_e32 v49, v32, v48
	v_mul_f32_e32 v48, v35, v51
	v_fmac_f32_e32 v33, v32, v94
	v_mul_f32_e32 v32, v35, v97
	v_fmac_f32_e32 v48, v34, v50
	v_fmac_f32_e32 v32, v34, v96
	v_add_f32_e32 v48, v49, v48
	v_add_f32_e32 v32, v33, v32
	v_mul_f32_e32 v33, v29, v41
	v_mul_f32_e32 v34, v31, v43
	v_add_f32_e32 v100, v102, v48
	ds_read_b128 v[48:51], v66 offset:912
	v_fmac_f32_e32 v33, v28, v40
	v_fmac_f32_e32 v34, v30, v42
	v_add_f32_e32 v33, v33, v34
	v_add_f32_e32 v40, v99, v33
	v_mul_f32_e32 v33, v29, v37
	v_mul_f32_e32 v34, v31, v39
	v_fmac_f32_e32 v33, v28, v36
	v_fmac_f32_e32 v34, v30, v38
	v_add_f32_e32 v33, v33, v34
	v_add_f32_e32 v93, v93, v33
	s_waitcnt lgkmcnt(1)
	v_mul_f32_e32 v33, v29, v45
	s_waitcnt lgkmcnt(0)
	v_mul_f32_e32 v29, v29, v49
	v_fmac_f32_e32 v33, v28, v44
	v_mul_f32_e32 v34, v31, v47
	v_fmac_f32_e32 v29, v28, v48
	v_mul_f32_e32 v28, v31, v51
	v_fmac_f32_e32 v34, v30, v46
	v_fmac_f32_e32 v28, v30, v50
	v_add_f32_e32 v32, v98, v32
	v_add_f32_e32 v33, v33, v34
	v_add_f32_e32 v28, v29, v28
	v_add_f32_e32 v94, v100, v33
	v_add_f32_e32 v48, v32, v28
	ds_read_b128 v[28:31], v66 offset:160
	ds_read_b128 v[32:35], v66 offset:176
	ds_read_b128 v[36:39], v66 offset:416
	ds_read_b128 v[44:47], v66 offset:928
	s_waitcnt lgkmcnt(3)
	v_mul_f32_e32 v29, v25, v29
	v_mul_f32_e32 v31, v27, v31
	s_waitcnt lgkmcnt(1)
	v_mul_f32_e32 v37, v25, v37
	v_fmac_f32_e32 v37, v24, v36
	v_mul_f32_e32 v36, v27, v39
	v_fmac_f32_e32 v29, v24, v28
	v_fmac_f32_e32 v31, v26, v30
	v_fmac_f32_e32 v36, v26, v38
	v_add_f32_e32 v28, v29, v31
	v_add_f32_e32 v36, v37, v36
	v_add_f32_e32 v49, v40, v28
	ds_read_b128 v[28:31], v66 offset:432
	ds_read_b128 v[40:43], v66 offset:672
	v_add_f32_e32 v50, v93, v36
	ds_read_b128 v[36:39], v66 offset:688
	s_waitcnt lgkmcnt(1)
	v_mul_f32_e32 v41, v25, v41
	v_mul_f32_e32 v25, v25, v45
	v_fmac_f32_e32 v41, v24, v40
	v_mul_f32_e32 v40, v27, v43
	v_fmac_f32_e32 v25, v24, v44
	v_mul_f32_e32 v24, v27, v47
	v_fmac_f32_e32 v40, v26, v42
	v_fmac_f32_e32 v24, v26, v46
	v_add_f32_e32 v40, v41, v40
	v_add_f32_e32 v24, v25, v24
	v_mul_f32_e32 v25, v21, v33
	v_mul_f32_e32 v26, v23, v35
	v_add_f32_e32 v51, v94, v40
	ds_read_b128 v[40:43], v66 offset:944
	v_fmac_f32_e32 v25, v20, v32
	v_fmac_f32_e32 v26, v22, v34
	v_add_f32_e32 v25, v25, v26
	v_add_f32_e32 v32, v49, v25
	v_mul_f32_e32 v25, v21, v29
	v_mul_f32_e32 v26, v23, v31
	v_fmac_f32_e32 v25, v20, v28
	v_fmac_f32_e32 v26, v22, v30
	v_add_f32_e32 v25, v25, v26
	v_add_f32_e32 v44, v50, v25
	s_waitcnt lgkmcnt(1)
	v_mul_f32_e32 v25, v21, v37
	s_waitcnt lgkmcnt(0)
	v_mul_f32_e32 v21, v21, v41
	v_fmac_f32_e32 v25, v20, v36
	v_fmac_f32_e32 v21, v20, v40
	v_mul_f32_e32 v20, v23, v43
	v_mul_f32_e32 v26, v23, v39
	v_fmac_f32_e32 v20, v22, v42
	v_add_f32_e32 v24, v48, v24
	v_fmac_f32_e32 v26, v22, v38
	v_add_f32_e32 v20, v21, v20
	v_add_f32_e32 v25, v25, v26
	v_add_f32_e32 v40, v24, v20
	v_add_f32_e32 v45, v51, v25
	ds_read_b128 v[20:23], v66 offset:192
	ds_read_b128 v[24:27], v66 offset:208
	ds_read_b128 v[28:31], v66 offset:448
	ds_read_b128 v[36:39], v66 offset:960
	s_waitcnt vmcnt(0) lgkmcnt(3)
	v_mul_f32_e32 v21, v17, v21
	v_mul_f32_e32 v23, v19, v23
	s_waitcnt lgkmcnt(1)
	v_mul_f32_e32 v29, v17, v29
	v_fmac_f32_e32 v29, v16, v28
	v_mul_f32_e32 v28, v19, v31
	v_fmac_f32_e32 v21, v16, v20
	v_fmac_f32_e32 v23, v18, v22
	v_fmac_f32_e32 v28, v18, v30
	v_add_f32_e32 v20, v21, v23
	v_add_f32_e32 v28, v29, v28
	v_add_f32_e32 v41, v32, v20
	ds_read_b128 v[20:23], v66 offset:464
	ds_read_b128 v[32:35], v66 offset:704
	v_add_f32_e32 v42, v44, v28
	ds_read_b128 v[28:31], v66 offset:720
	s_waitcnt lgkmcnt(1)
	v_mul_f32_e32 v33, v17, v33
	v_mul_f32_e32 v17, v17, v37
	v_fmac_f32_e32 v33, v16, v32
	v_mul_f32_e32 v32, v19, v35
	v_fmac_f32_e32 v17, v16, v36
	v_mul_f32_e32 v16, v19, v39
	v_fmac_f32_e32 v32, v18, v34
	v_fmac_f32_e32 v16, v18, v38
	v_add_f32_e32 v32, v33, v32
	v_add_f32_e32 v16, v17, v16
	v_mul_f32_e32 v17, v13, v25
	v_mul_f32_e32 v18, v15, v27
	v_add_f32_e32 v43, v45, v32
	ds_read_b128 v[32:35], v66 offset:976
	v_fmac_f32_e32 v17, v12, v24
	v_fmac_f32_e32 v18, v14, v26
	v_add_f32_e32 v17, v17, v18
	v_add_f32_e32 v24, v41, v17
	v_mul_f32_e32 v17, v13, v21
	v_mul_f32_e32 v18, v15, v23
	v_fmac_f32_e32 v17, v12, v20
	v_fmac_f32_e32 v18, v14, v22
	v_add_f32_e32 v17, v17, v18
	v_add_f32_e32 v36, v42, v17
	s_waitcnt lgkmcnt(1)
	v_mul_f32_e32 v17, v13, v29
	s_waitcnt lgkmcnt(0)
	v_mul_f32_e32 v13, v13, v33
	v_fmac_f32_e32 v17, v12, v28
	v_mul_f32_e32 v18, v15, v31
	v_fmac_f32_e32 v13, v12, v32
	v_mul_f32_e32 v12, v15, v35
	v_fmac_f32_e32 v18, v14, v30
	v_fmac_f32_e32 v12, v14, v34
	v_add_f32_e32 v16, v40, v16
	v_add_f32_e32 v17, v17, v18
	v_add_f32_e32 v12, v13, v12
	v_add_f32_e32 v37, v43, v17
	v_add_f32_e32 v32, v16, v12
	ds_read_b128 v[12:15], v66 offset:224
	ds_read_b128 v[16:19], v66 offset:240
	ds_read_b128 v[20:23], v66 offset:480
	ds_read_b128 v[28:31], v66 offset:992
	s_waitcnt lgkmcnt(3)
	v_mul_f32_e32 v13, v9, v13
	v_mul_f32_e32 v15, v11, v15
	s_waitcnt lgkmcnt(1)
	v_mul_f32_e32 v21, v9, v21
	v_fmac_f32_e32 v21, v8, v20
	v_mul_f32_e32 v20, v11, v23
	v_fmac_f32_e32 v13, v8, v12
	v_fmac_f32_e32 v15, v10, v14
	v_fmac_f32_e32 v20, v10, v22
	v_add_f32_e32 v12, v13, v15
	v_add_f32_e32 v20, v21, v20
	v_add_f32_e32 v33, v24, v12
	ds_read_b128 v[12:15], v66 offset:496
	ds_read_b128 v[24:27], v66 offset:736
	v_add_f32_e32 v34, v36, v20
	ds_read_b128 v[20:23], v66 offset:752
	s_waitcnt lgkmcnt(1)
	v_mul_f32_e32 v25, v9, v25
	v_mul_f32_e32 v9, v9, v29
	v_fmac_f32_e32 v25, v8, v24
	v_mul_f32_e32 v24, v11, v27
	v_fmac_f32_e32 v9, v8, v28
	v_mul_f32_e32 v8, v11, v31
	v_fmac_f32_e32 v24, v10, v26
	v_fmac_f32_e32 v8, v10, v30
	v_add_f32_e32 v24, v25, v24
	v_add_f32_e32 v8, v9, v8
	v_mul_f32_e32 v9, v5, v17
	v_mul_f32_e32 v10, v7, v19
	v_add_f32_e32 v35, v37, v24
	ds_read_b128 v[24:27], v66 offset:1008
	v_fmac_f32_e32 v9, v4, v16
	v_fmac_f32_e32 v10, v6, v18
	v_add_f32_e32 v9, v9, v10
	v_add_f32_e32 v93, v33, v9
	v_mul_f32_e32 v9, v5, v13
	v_mul_f32_e32 v10, v7, v15
	v_fmac_f32_e32 v9, v4, v12
	v_fmac_f32_e32 v10, v6, v14
	v_add_f32_e32 v9, v9, v10
	v_add_f32_e32 v94, v34, v9
	s_waitcnt lgkmcnt(1)
	v_mul_f32_e32 v9, v5, v21
	s_waitcnt lgkmcnt(0)
	v_mul_f32_e32 v5, v5, v25
	v_fmac_f32_e32 v9, v4, v20
	v_mul_f32_e32 v10, v7, v23
	v_fmac_f32_e32 v5, v4, v24
	v_mul_f32_e32 v4, v7, v27
	v_fmac_f32_e32 v10, v6, v22
	v_fmac_f32_e32 v4, v6, v26
	v_add_f32_e32 v8, v32, v8
	v_add_f32_e32 v9, v9, v10
	v_add_f32_e32 v4, v5, v4
	v_add_f32_e32 v95, v35, v9
	v_add_f32_e32 v96, v8, v4
	v_or_b32_e32 v4, v62, v69
	v_ashrrev_i32_e32 v5, 31, v4
	v_lshlrev_b64 v[4:5], 10, v[4:5]
	v_lshl_add_u64 v[4:5], s[30:31], 0, v[4:5]
	v_lshl_add_u64 v[16:17], v[4:5], 0, v[54:55]
	global_load_dwordx4 v[98:101], v[16:17], off nt
	global_load_dwordx4 v[102:105], v[16:17], off offset:16 nt
	global_load_dwordx4 v[106:109], v[16:17], off offset:48 nt
	global_load_dwordx4 v[110:113], v[16:17], off offset:32 nt
	global_load_dwordx4 v[36:39], v[16:17], off offset:112 nt
	global_load_dwordx4 v[40:43], v[16:17], off offset:96 nt
	global_load_dwordx4 v[44:47], v[16:17], off offset:80 nt
	global_load_dwordx4 v[48:51], v[16:17], off offset:64 nt
	global_load_dwordx4 v[20:23], v[16:17], off offset:176 nt
	global_load_dwordx4 v[24:27], v[16:17], off offset:160 nt
	global_load_dwordx4 v[28:31], v[16:17], off offset:144 nt
	global_load_dwordx4 v[32:35], v[16:17], off offset:128 nt
	global_load_dwordx4 v[4:7], v[16:17], off offset:240 nt
	global_load_dwordx4 v[8:11], v[16:17], off offset:224 nt
	global_load_dwordx4 v[12:15], v[16:17], off offset:208 nt
	s_nop 0
	global_load_dwordx4 v[16:19], v[16:17], off offset:192 nt
	v_fma_f32 v93, -v89, v68, v93
	v_fma_f32 v114, -v92, v68, v96
	v_cndmask_b32_e64 v96, v93, v76, s[2:3]
	v_cndmask_b32_e64 v93, v114, v76, s[2:3]
	ds_read_b128 v[114:117], v66
	ds_read_b128 v[118:121], v66 offset:16
	ds_read_b128 v[122:125], v66 offset:256
	ds_read_b128 v[126:129], v66 offset:768
	ds_read_b128 v[130:133], v66 offset:784
	ds_read_b128 v[134:137], v66 offset:512
	ds_read_b128 v[138:141], v66 offset:528
	ds_read_b128 v[142:145], v66 offset:272
	v_fma_f32 v94, -v90, v68, v94
	v_fma_f32 v97, -v91, v68, v95
	v_cndmask_b32_e64 v95, v94, v76, s[2:3]
	v_cndmask_b32_e64 v94, v97, v76, s[2:3]
	s_waitcnt vmcnt(15) lgkmcnt(7)
	v_mul_f32_e32 v97, v99, v115
	v_mul_f32_e32 v115, v101, v117
	s_waitcnt lgkmcnt(5)
	v_mul_f32_e32 v117, v99, v123
	v_mul_f32_e32 v123, v101, v125
	s_waitcnt lgkmcnt(2)
	v_mul_f32_e32 v125, v99, v135
	v_mul_f32_e32 v135, v101, v137
	v_mul_f32_e32 v99, v99, v127
	v_mul_f32_e32 v101, v101, v129
	s_waitcnt vmcnt(14)
	v_mul_f32_e32 v119, v103, v119
	v_mul_f32_e32 v121, v105, v121
	s_waitcnt lgkmcnt(0)
	v_mul_f32_e32 v127, v103, v143
	v_mul_f32_e32 v129, v105, v145
	v_mul_f32_e32 v137, v103, v139
	v_mul_f32_e32 v139, v105, v141
	v_mul_f32_e32 v103, v103, v131
	v_mul_f32_e32 v105, v105, v133
	v_fmac_f32_e32 v97, v98, v114
	v_fmac_f32_e32 v115, v100, v116
	v_fmac_f32_e32 v117, v98, v122
	v_fmac_f32_e32 v123, v100, v124
	v_fmac_f32_e32 v125, v98, v134
	v_fmac_f32_e32 v135, v100, v136
	v_fmac_f32_e32 v99, v98, v126
	v_fmac_f32_e32 v101, v100, v128
	v_fmac_f32_e32 v119, v102, v118
	v_fmac_f32_e32 v121, v104, v120
	v_fmac_f32_e32 v127, v102, v142
	v_fmac_f32_e32 v129, v104, v144
	v_fmac_f32_e32 v137, v102, v138
	v_fmac_f32_e32 v139, v104, v140
	v_fmac_f32_e32 v103, v102, v130
	v_fmac_f32_e32 v105, v104, v132
	v_add_f32_e32 v97, v97, v115
	v_add_f32_e32 v98, v117, v123
	v_add_f32_e32 v100, v125, v135
	v_add_f32_e32 v99, v99, v101
	v_add_f32_e32 v101, v119, v121
	v_add_f32_e32 v102, v127, v129
	v_add_f32_e32 v104, v137, v139
	v_add_f32_e32 v103, v103, v105
	v_add_f32_e32 v97, 0, v97
	v_add_f32_e32 v98, 0, v98
	v_add_f32_e32 v100, 0, v100
	v_add_f32_e32 v99, 0, v99
	v_add_f32_e32 v97, v97, v101
	v_add_f32_e32 v122, v98, v102
	v_add_f32_e32 v126, v100, v104
	v_add_f32_e32 v127, v99, v103
	ds_read_b128 v[98:101], v66 offset:32
	ds_read_b128 v[102:105], v66 offset:48
	ds_read_b128 v[114:117], v66 offset:288
	ds_read_b128 v[118:121], v66 offset:544
	s_waitcnt vmcnt(12) lgkmcnt(3)
	v_mul_f32_e32 v99, v111, v99
	v_mul_f32_e32 v101, v113, v101
	v_fmac_f32_e32 v99, v110, v98
	v_fmac_f32_e32 v101, v112, v100
	v_add_f32_e32 v98, v99, v101
	v_add_f32_e32 v97, v97, v98
	ds_read_b128 v[98:101], v66 offset:304
	s_waitcnt lgkmcnt(2)
	v_mul_f32_e32 v115, v111, v115
	v_fmac_f32_e32 v115, v110, v114
	v_mul_f32_e32 v114, v113, v117
	v_fmac_f32_e32 v114, v112, v116
	v_add_f32_e32 v114, v115, v114
	v_add_f32_e32 v128, v122, v114
	ds_read_b128 v[114:117], v66 offset:560
	ds_read_b128 v[122:125], v66 offset:800
	s_waitcnt lgkmcnt(3)
	v_mul_f32_e32 v119, v111, v119
	v_fmac_f32_e32 v119, v110, v118
	v_mul_f32_e32 v118, v113, v121
	v_fmac_f32_e32 v118, v112, v120
	s_waitcnt lgkmcnt(2)
	v_mul_f32_e32 v99, v107, v99
	v_add_f32_e32 v118, v119, v118
	v_fmac_f32_e32 v99, v106, v98
	v_mul_f32_e32 v98, v109, v101
	v_add_f32_e32 v126, v126, v118
	ds_read_b128 v[118:121], v66 offset:816
	v_fmac_f32_e32 v98, v108, v100
	s_waitcnt lgkmcnt(1)
	v_mul_f32_e32 v111, v111, v123
	v_add_f32_e32 v98, v99, v98
	v_fmac_f32_e32 v111, v110, v122
	v_add_f32_e32 v122, v128, v98
	v_mul_f32_e32 v98, v107, v115
	v_mul_f32_e32 v99, v109, v117
	v_fmac_f32_e32 v98, v106, v114
	v_fmac_f32_e32 v99, v108, v116
	v_mul_f32_e32 v110, v113, v125
	v_mul_f32_e32 v103, v107, v103
	v_add_f32_e32 v98, v98, v99
	v_fmac_f32_e32 v110, v112, v124
	v_fmac_f32_e32 v103, v106, v102
	v_mul_f32_e32 v102, v109, v105
	v_add_f32_e32 v123, v126, v98
	s_waitcnt lgkmcnt(0)
	v_mul_f32_e32 v98, v107, v119
	v_mul_f32_e32 v99, v109, v121
	v_add_f32_e32 v110, v111, v110
	v_fmac_f32_e32 v102, v108, v104
	v_fmac_f32_e32 v98, v106, v118
	v_fmac_f32_e32 v99, v108, v120
	v_add_f32_e32 v110, v127, v110
	v_add_f32_e32 v102, v103, v102
	v_add_f32_e32 v98, v98, v99
	v_add_f32_e32 v97, v97, v102
	v_add_f32_e32 v118, v110, v98
	ds_read_b128 v[98:101], v66 offset:64
	ds_read_b128 v[102:105], v66 offset:80
	ds_read_b128 v[106:109], v66 offset:320
	ds_read_b128 v[110:113], v66 offset:576
	ds_read_b128 v[114:117], v66 offset:832
	s_waitcnt vmcnt(8) lgkmcnt(4)
	v_mul_f32_e32 v99, v49, v99
	v_mul_f32_e32 v101, v51, v101
	s_waitcnt lgkmcnt(2)
	v_mul_f32_e32 v107, v49, v107
	v_fmac_f32_e32 v107, v48, v106
	v_mul_f32_e32 v106, v51, v109
	v_fmac_f32_e32 v99, v48, v98
	v_fmac_f32_e32 v101, v50, v100
	v_fmac_f32_e32 v106, v50, v108
	v_add_f32_e32 v98, v99, v101
	v_add_f32_e32 v106, v107, v106
	v_add_f32_e32 v97, v97, v98
	ds_read_b128 v[98:101], v66 offset:336
	v_add_f32_e32 v119, v122, v106
	ds_read_b128 v[106:109], v66 offset:592
	s_waitcnt lgkmcnt(3)
	v_mul_f32_e32 v111, v49, v111
	s_waitcnt lgkmcnt(2)
	v_mul_f32_e32 v49, v49, v115
	v_fmac_f32_e32 v111, v48, v110
	v_mul_f32_e32 v110, v51, v113
	v_fmac_f32_e32 v49, v48, v114
	v_mul_f32_e32 v48, v51, v117
	v_fmac_f32_e32 v110, v50, v112
	v_fmac_f32_e32 v48, v50, v116
	v_add_f32_e32 v110, v111, v110
	v_add_f32_e32 v48, v49, v48
	v_mul_f32_e32 v49, v45, v103
	v_mul_f32_e32 v50, v47, v105
	v_add_f32_e32 v120, v123, v110
	ds_read_b128 v[110:113], v66 offset:848
	v_fmac_f32_e32 v49, v44, v102
	v_fmac_f32_e32 v50, v46, v104
	v_add_f32_e32 v49, v49, v50
	v_add_f32_e32 v97, v97, v49
	s_waitcnt lgkmcnt(2)
	v_mul_f32_e32 v49, v45, v99
	v_mul_f32_e32 v50, v47, v101
	v_fmac_f32_e32 v49, v44, v98
	v_fmac_f32_e32 v50, v46, v100
	v_add_f32_e32 v49, v49, v50
	v_add_f32_e32 v114, v119, v49
	s_waitcnt lgkmcnt(1)
	v_mul_f32_e32 v49, v45, v107
	s_waitcnt lgkmcnt(0)
	v_mul_f32_e32 v45, v45, v111
	v_fmac_f32_e32 v49, v44, v106
	v_mul_f32_e32 v50, v47, v109
	v_fmac_f32_e32 v45, v44, v110
	v_mul_f32_e32 v44, v47, v113
	v_fmac_f32_e32 v50, v46, v108
	v_fmac_f32_e32 v44, v46, v112
	v_add_f32_e32 v48, v118, v48
	v_add_f32_e32 v49, v49, v50
	v_add_f32_e32 v44, v45, v44
	v_add_f32_e32 v115, v120, v49
	v_add_f32_e32 v110, v48, v44
	ds_read_b128 v[44:47], v66 offset:96
	ds_read_b128 v[48:51], v66 offset:112
	ds_read_b128 v[98:101], v66 offset:352
	ds_read_b128 v[102:105], v66 offset:608
	ds_read_b128 v[106:109], v66 offset:864
	s_waitcnt lgkmcnt(4)
	v_mul_f32_e32 v45, v41, v45
	v_mul_f32_e32 v47, v43, v47
	s_waitcnt lgkmcnt(2)
	v_mul_f32_e32 v99, v41, v99
	v_fmac_f32_e32 v99, v40, v98
	v_mul_f32_e32 v98, v43, v101
	v_fmac_f32_e32 v45, v40, v44
	v_fmac_f32_e32 v47, v42, v46
	v_fmac_f32_e32 v98, v42, v100
	v_add_f32_e32 v44, v45, v47
	v_add_f32_e32 v98, v99, v98
	v_add_f32_e32 v97, v97, v44
	ds_read_b128 v[44:47], v66 offset:368
	v_add_f32_e32 v111, v114, v98
	ds_read_b128 v[98:101], v66 offset:624
	s_waitcnt lgkmcnt(3)
	v_mul_f32_e32 v103, v41, v103
	s_waitcnt lgkmcnt(2)
	v_mul_f32_e32 v41, v41, v107
	v_fmac_f32_e32 v103, v40, v102
	v_mul_f32_e32 v102, v43, v105
	v_fmac_f32_e32 v41, v40, v106
	v_mul_f32_e32 v40, v43, v109
	v_fmac_f32_e32 v102, v42, v104
	v_fmac_f32_e32 v40, v42, v108
	v_add_f32_e32 v102, v103, v102
	v_add_f32_e32 v40, v41, v40
	v_mul_f32_e32 v41, v37, v49
	v_mul_f32_e32 v42, v39, v51
	v_add_f32_e32 v112, v115, v102
	ds_read_b128 v[102:105], v66 offset:880
	v_fmac_f32_e32 v41, v36, v48
	v_fmac_f32_e32 v42, v38, v50
	v_add_f32_e32 v41, v41, v42
	v_add_f32_e32 v48, v97, v41
	s_waitcnt lgkmcnt(2)
	v_mul_f32_e32 v41, v37, v45
	v_mul_f32_e32 v42, v39, v47
	v_fmac_f32_e32 v41, v36, v44
	v_fmac_f32_e32 v42, v38, v46
	v_add_f32_e32 v41, v41, v42
	v_add_f32_e32 v97, v111, v41
	s_waitcnt lgkmcnt(1)
	v_mul_f32_e32 v41, v37, v99
	s_waitcnt lgkmcnt(0)
	v_mul_f32_e32 v37, v37, v103
	v_fmac_f32_e32 v41, v36, v98
	v_mul_f32_e32 v42, v39, v101
	v_fmac_f32_e32 v37, v36, v102
	v_mul_f32_e32 v36, v39, v105
	v_fmac_f32_e32 v42, v38, v100
	v_fmac_f32_e32 v36, v38, v104
	v_add_f32_e32 v40, v110, v40
	v_add_f32_e32 v41, v41, v42
	v_add_f32_e32 v36, v37, v36
	v_add_f32_e32 v106, v112, v41
	v_add_f32_e32 v102, v40, v36
	ds_read_b128 v[36:39], v66 offset:128
	ds_read_b128 v[40:43], v66 offset:144
	ds_read_b128 v[44:47], v66 offset:384
	ds_read_b128 v[98:101], v66 offset:896
	s_waitcnt vmcnt(4) lgkmcnt(3)
	v_mul_f32_e32 v37, v33, v37
	v_mul_f32_e32 v39, v35, v39
	s_waitcnt lgkmcnt(1)
	v_mul_f32_e32 v45, v33, v45
	v_fmac_f32_e32 v45, v32, v44
	v_mul_f32_e32 v44, v35, v47
	v_fmac_f32_e32 v37, v32, v36
	v_fmac_f32_e32 v39, v34, v38
	v_fmac_f32_e32 v44, v34, v46
	v_add_f32_e32 v36, v37, v39
	v_add_f32_e32 v44, v45, v44
	v_add_f32_e32 v103, v48, v36
	ds_read_b128 v[36:39], v66 offset:400
	ds_read_b128 v[48:51], v66 offset:640
	v_add_f32_e32 v97, v97, v44
	ds_read_b128 v[44:47], v66 offset:656
	s_waitcnt lgkmcnt(1)
	v_mul_f32_e32 v49, v33, v49
	v_mul_f32_e32 v33, v33, v99
	v_fmac_f32_e32 v49, v32, v48
	v_mul_f32_e32 v48, v35, v51
	v_fmac_f32_e32 v33, v32, v98
	v_mul_f32_e32 v32, v35, v101
	v_fmac_f32_e32 v48, v34, v50
	v_fmac_f32_e32 v32, v34, v100
	v_add_f32_e32 v48, v49, v48
	v_add_f32_e32 v32, v33, v32
	v_mul_f32_e32 v33, v29, v41
	v_mul_f32_e32 v34, v31, v43
	v_add_f32_e32 v104, v106, v48
	ds_read_b128 v[48:51], v66 offset:912
	v_fmac_f32_e32 v33, v28, v40
	v_fmac_f32_e32 v34, v30, v42
	v_add_f32_e32 v33, v33, v34
	v_add_f32_e32 v40, v103, v33
	v_mul_f32_e32 v33, v29, v37
	v_mul_f32_e32 v34, v31, v39
	v_fmac_f32_e32 v33, v28, v36
	v_fmac_f32_e32 v34, v30, v38
	v_add_f32_e32 v33, v33, v34
	v_add_f32_e32 v97, v97, v33
	s_waitcnt lgkmcnt(1)
	v_mul_f32_e32 v33, v29, v45
	s_waitcnt lgkmcnt(0)
	v_mul_f32_e32 v29, v29, v49
	v_fmac_f32_e32 v33, v28, v44
	v_mul_f32_e32 v34, v31, v47
	v_fmac_f32_e32 v29, v28, v48
	v_mul_f32_e32 v28, v31, v51
	v_fmac_f32_e32 v34, v30, v46
	v_fmac_f32_e32 v28, v30, v50
	v_add_f32_e32 v32, v102, v32
	v_add_f32_e32 v33, v33, v34
	v_add_f32_e32 v28, v29, v28
	v_add_f32_e32 v98, v104, v33
	v_add_f32_e32 v48, v32, v28
	ds_read_b128 v[28:31], v66 offset:160
	ds_read_b128 v[32:35], v66 offset:176
	ds_read_b128 v[36:39], v66 offset:416
	ds_read_b128 v[44:47], v66 offset:928
	s_waitcnt lgkmcnt(3)
	v_mul_f32_e32 v29, v25, v29
	v_mul_f32_e32 v31, v27, v31
	s_waitcnt lgkmcnt(1)
	v_mul_f32_e32 v37, v25, v37
	v_fmac_f32_e32 v37, v24, v36
	v_mul_f32_e32 v36, v27, v39
	v_fmac_f32_e32 v29, v24, v28
	v_fmac_f32_e32 v31, v26, v30
	v_fmac_f32_e32 v36, v26, v38
	v_add_f32_e32 v28, v29, v31
	v_add_f32_e32 v36, v37, v36
	v_add_f32_e32 v49, v40, v28
	ds_read_b128 v[28:31], v66 offset:432
	ds_read_b128 v[40:43], v66 offset:672
	v_add_f32_e32 v50, v97, v36
	ds_read_b128 v[36:39], v66 offset:688
	s_waitcnt lgkmcnt(1)
	v_mul_f32_e32 v41, v25, v41
	v_mul_f32_e32 v25, v25, v45
	v_fmac_f32_e32 v41, v24, v40
	v_mul_f32_e32 v40, v27, v43
	v_fmac_f32_e32 v25, v24, v44
	v_mul_f32_e32 v24, v27, v47
	v_fmac_f32_e32 v40, v26, v42
	v_fmac_f32_e32 v24, v26, v46
	v_add_f32_e32 v40, v41, v40
	v_add_f32_e32 v24, v25, v24
	v_mul_f32_e32 v25, v21, v33
	v_mul_f32_e32 v26, v23, v35
	v_add_f32_e32 v51, v98, v40
	ds_read_b128 v[40:43], v66 offset:944
	v_fmac_f32_e32 v25, v20, v32
	v_fmac_f32_e32 v26, v22, v34
	v_add_f32_e32 v25, v25, v26
	v_add_f32_e32 v32, v49, v25
	v_mul_f32_e32 v25, v21, v29
	v_mul_f32_e32 v26, v23, v31
	v_fmac_f32_e32 v25, v20, v28
	v_fmac_f32_e32 v26, v22, v30
	v_add_f32_e32 v25, v25, v26
	v_add_f32_e32 v44, v50, v25
	s_waitcnt lgkmcnt(1)
	v_mul_f32_e32 v25, v21, v37
	s_waitcnt lgkmcnt(0)
	v_mul_f32_e32 v21, v21, v41
	v_fmac_f32_e32 v25, v20, v36
	v_fmac_f32_e32 v21, v20, v40
	v_mul_f32_e32 v20, v23, v43
	v_mul_f32_e32 v26, v23, v39
	v_fmac_f32_e32 v20, v22, v42
	v_add_f32_e32 v24, v48, v24
	v_fmac_f32_e32 v26, v22, v38
	v_add_f32_e32 v20, v21, v20
	v_add_f32_e32 v25, v25, v26
	v_add_f32_e32 v40, v24, v20
	v_add_f32_e32 v45, v51, v25
	ds_read_b128 v[20:23], v66 offset:192
	ds_read_b128 v[24:27], v66 offset:208
	ds_read_b128 v[28:31], v66 offset:448
	ds_read_b128 v[36:39], v66 offset:960
	s_waitcnt vmcnt(0) lgkmcnt(3)
	v_mul_f32_e32 v21, v17, v21
	v_mul_f32_e32 v23, v19, v23
	s_waitcnt lgkmcnt(1)
	v_mul_f32_e32 v29, v17, v29
	v_fmac_f32_e32 v29, v16, v28
	v_mul_f32_e32 v28, v19, v31
	v_fmac_f32_e32 v21, v16, v20
	v_fmac_f32_e32 v23, v18, v22
	v_fmac_f32_e32 v28, v18, v30
	v_add_f32_e32 v20, v21, v23
	v_add_f32_e32 v28, v29, v28
	v_add_f32_e32 v41, v32, v20
	ds_read_b128 v[20:23], v66 offset:464
	ds_read_b128 v[32:35], v66 offset:704
	v_add_f32_e32 v42, v44, v28
	ds_read_b128 v[28:31], v66 offset:720
	s_waitcnt lgkmcnt(1)
	v_mul_f32_e32 v33, v17, v33
	v_mul_f32_e32 v17, v17, v37
	v_fmac_f32_e32 v33, v16, v32
	v_mul_f32_e32 v32, v19, v35
	v_fmac_f32_e32 v17, v16, v36
	v_mul_f32_e32 v16, v19, v39
	v_fmac_f32_e32 v32, v18, v34
	v_fmac_f32_e32 v16, v18, v38
	v_add_f32_e32 v32, v33, v32
	v_add_f32_e32 v16, v17, v16
	v_mul_f32_e32 v17, v13, v25
	v_mul_f32_e32 v18, v15, v27
	v_add_f32_e32 v43, v45, v32
	ds_read_b128 v[32:35], v66 offset:976
	v_fmac_f32_e32 v17, v12, v24
	v_fmac_f32_e32 v18, v14, v26
	v_add_f32_e32 v17, v17, v18
	v_add_f32_e32 v24, v41, v17
	v_mul_f32_e32 v17, v13, v21
	v_mul_f32_e32 v18, v15, v23
	v_fmac_f32_e32 v17, v12, v20
	v_fmac_f32_e32 v18, v14, v22
	v_add_f32_e32 v17, v17, v18
	v_add_f32_e32 v36, v42, v17
	s_waitcnt lgkmcnt(1)
	v_mul_f32_e32 v17, v13, v29
	s_waitcnt lgkmcnt(0)
	v_mul_f32_e32 v13, v13, v33
	v_fmac_f32_e32 v17, v12, v28
	v_mul_f32_e32 v18, v15, v31
	v_fmac_f32_e32 v13, v12, v32
	v_mul_f32_e32 v12, v15, v35
	v_fmac_f32_e32 v18, v14, v30
	v_fmac_f32_e32 v12, v14, v34
	v_add_f32_e32 v16, v40, v16
	v_add_f32_e32 v17, v17, v18
	v_add_f32_e32 v12, v13, v12
	v_add_f32_e32 v37, v43, v17
	v_add_f32_e32 v32, v16, v12
	ds_read_b128 v[12:15], v66 offset:224
	ds_read_b128 v[16:19], v66 offset:240
	ds_read_b128 v[20:23], v66 offset:480
	ds_read_b128 v[28:31], v66 offset:992
	s_waitcnt lgkmcnt(3)
	v_mul_f32_e32 v13, v9, v13
	v_mul_f32_e32 v15, v11, v15
	v_fmac_f32_e32 v13, v8, v12
	v_fmac_f32_e32 v15, v10, v14
	s_waitcnt lgkmcnt(1)
	v_mul_f32_e32 v21, v9, v21
	v_add_f32_e32 v12, v13, v15
	v_fmac_f32_e32 v21, v8, v20
	v_mul_f32_e32 v20, v11, v23
	v_add_f32_e32 v33, v24, v12
	ds_read_b128 v[12:15], v66 offset:496
	ds_read_b128 v[24:27], v66 offset:736
	v_fmac_f32_e32 v20, v10, v22
	v_add_f32_e32 v20, v21, v20
	v_add_f32_e32 v34, v36, v20
	ds_read_b128 v[20:23], v66 offset:752
	s_waitcnt lgkmcnt(1)
	v_mul_f32_e32 v25, v9, v25
	v_fmac_f32_e32 v25, v8, v24
	v_mul_f32_e32 v24, v11, v27
	v_fmac_f32_e32 v24, v10, v26
	v_mul_f32_e32 v9, v9, v29
	v_add_f32_e32 v24, v25, v24
	v_fmac_f32_e32 v9, v8, v28
	v_mul_f32_e32 v8, v11, v31
	v_add_f32_e32 v35, v37, v24
	ds_read_b128 v[24:27], v66 offset:1008
	v_fmac_f32_e32 v8, v10, v30
	v_add_f32_e32 v8, v9, v8
	v_mul_f32_e32 v9, v5, v17
	v_mul_f32_e32 v10, v7, v19
	v_fmac_f32_e32 v9, v4, v16
	v_fmac_f32_e32 v10, v6, v18
	v_add_f32_e32 v9, v9, v10
	v_mul_f32_e32 v10, v5, v13
	v_mul_f32_e32 v11, v7, v15
	v_fmac_f32_e32 v10, v4, v12
	v_fmac_f32_e32 v11, v6, v14
	v_add_f32_e32 v10, v10, v11
	s_waitcnt lgkmcnt(1)
	v_mul_f32_e32 v11, v5, v21
	s_waitcnt lgkmcnt(0)
	v_mul_f32_e32 v5, v5, v25
	v_fmac_f32_e32 v11, v4, v20
	v_mul_f32_e32 v12, v7, v23
	v_fmac_f32_e32 v5, v4, v24
	v_mul_f32_e32 v4, v7, v27
	v_fmac_f32_e32 v12, v6, v22
	v_fmac_f32_e32 v4, v6, v26
	v_add_f32_e32 v8, v32, v8
	v_add_f32_e32 v11, v11, v12
	v_add_f32_e32 v4, v5, v4
	v_add_f32_e32 v9, v33, v9
	v_add_f32_e32 v10, v34, v10
	v_add_f32_e32 v11, v35, v11
	v_add_f32_e32 v8, v8, v4
	v_lshlrev_b64 v[4:5], 8, v[64:65]
	v_lshl_or_b32 v4, v63, 6, v4
	v_or_b32_e32 v4, v4, v52
	v_lshlrev_b64 v[4:5], 1, v[4:5]
	v_lshl_add_u64 v[6:7], s[6:7], 0, v[4:5]
	flat_load_ushort v12, v[6:7]
	v_lshl_add_u64 v[4:5], s[26:27], 0, v[4:5]
	flat_load_ushort v21, v[4:5]
	v_cmp_lt_i32_e32 vcc, v79, v78
	v_fma_f32 v9, -v89, v70, v9
	v_fma_f32 v10, -v90, v70, v10
	v_cndmask_b32_e32 v6, v77, v79, vcc
	v_cmp_lt_i32_e32 vcc, v80, v78
	v_lshlrev_b32_e32 v19, 2, v6
	v_max_f32_e32 v6, v96, v9
	v_cndmask_b32_e32 v7, v77, v80, vcc
	v_max_f32_e32 v4, v95, v10
	v_lshlrev_b32_e32 v20, 2, v7
	ds_bpermute_b32 v5, v19, v6
	ds_bpermute_b32 v7, v19, v4
	v_cmp_lt_i32_e32 vcc, v81, v78
	v_fma_f32 v11, -v91, v70, v11
	v_max_f32_e32 v17, v0, v0
	v_cndmask_b32_e32 v13, v77, v81, vcc
	v_cmp_lt_i32_e32 vcc, v82, v78
	s_waitcnt lgkmcnt(0)
	v_max_f32_e32 v5, v5, v5
	v_max_f32_e32 v7, v7, v7
	v_cndmask_b32_e32 v14, v77, v82, vcc
	v_cmp_lt_i32_e32 vcc, v83, v78
	v_max_f32_e32 v5, v6, v5
	v_max_f32_e32 v4, v4, v7
	v_cndmask_b32_e32 v15, v77, v83, vcc
	v_cmp_lt_i32_e32 vcc, v84, v78
	ds_bpermute_b32 v6, v20, v5
	ds_bpermute_b32 v7, v20, v4
	v_cndmask_b32_e32 v16, v77, v84, vcc
	v_lshlrev_b32_e32 v28, 2, v16
	v_max_f32_e32 v16, v94, v11
	ds_bpermute_b32 v22, v19, v16
	s_waitcnt lgkmcnt(0)
	v_max_f32_e32 v6, v6, v6
	v_max_f32_e32 v7, v7, v7
	v_lshlrev_b32_e32 v13, 2, v13
	v_max_f32_e32 v5, v5, v6
	v_max_f32_e32 v22, v22, v22
	v_max_f32_e32 v16, v16, v22
	v_max_f32_e32 v4, v4, v7
	ds_bpermute_b32 v22, v20, v16
	ds_bpermute_b32 v6, v13, v5
	ds_bpermute_b32 v7, v13, v4
	v_lshlrev_b32_e32 v14, 2, v14
	v_lshlrev_b32_e32 v15, 2, v15
	s_waitcnt lgkmcnt(0)
	v_max_f32_e32 v22, v22, v22
	v_max_f32_e32 v6, v6, v6
	v_max_f32_e32 v7, v7, v7
	v_max_f32_e32 v16, v16, v22
	v_max_f32_e32 v5, v5, v6
	v_max_f32_e32 v4, v4, v7
	ds_bpermute_b32 v22, v13, v16
	ds_bpermute_b32 v6, v14, v5
	ds_bpermute_b32 v7, v14, v4
	v_max_f32_e32 v18, v1, v1
	v_fma_f32 v8, -v92, v70, v8
	s_waitcnt lgkmcnt(0)
	v_max_f32_e32 v22, v22, v22
	v_max_f32_e32 v6, v6, v6
	v_max_f32_e32 v7, v7, v7
	v_max_f32_e32 v22, v16, v22
	v_max_f32_e32 v23, v5, v6
	v_max_f32_e32 v24, v4, v7
	ds_bpermute_b32 v16, v14, v22
	ds_bpermute_b32 v25, v15, v23
	ds_bpermute_b32 v26, v15, v24
	ds_read2st64_b32 v[4:5], v71 offset1:1
	ds_read2st64_b32 v[6:7], v71 offset0:2 offset1:3
	v_ashrrev_i32_e32 v63, 31, v62
	s_waitcnt lgkmcnt(0)
	v_max_f32_e32 v27, v16, v16
	v_max_f32_e32 v16, v25, v25
	v_max_f32_e32 v25, v26, v26
	v_max_f32_e32 v16, v23, v16
	v_max_f32_e32 v24, v24, v25
	ds_bpermute_b32 v30, v28, v24
	v_mov_b32_e32 v41, v72
	s_mov_b64 s[0:1], 0
	s_waitcnt vmcnt(0)
	v_lshlrev_b32_e32 v12, 16, v12
	v_mul_f32_e32 v26, v4, v12
	v_mul_f32_e32 v29, v5, v12
	ds_bpermute_b32 v26, v19, v26
	ds_bpermute_b32 v29, v19, v29
	v_mul_f32_e32 v23, v6, v12
	ds_bpermute_b32 v23, v19, v23
	s_waitcnt lgkmcnt(2)
	v_fmac_f32_e32 v26, v4, v12
	s_waitcnt lgkmcnt(1)
	v_fmac_f32_e32 v29, v5, v12
	ds_bpermute_b32 v4, v20, v26
	ds_bpermute_b32 v5, v20, v29
	s_waitcnt lgkmcnt(2)
	v_fmac_f32_e32 v23, v6, v12
	ds_bpermute_b32 v6, v20, v23
	s_waitcnt lgkmcnt(2)
	v_add_f32_e32 v4, v26, v4
	s_waitcnt lgkmcnt(1)
	v_add_f32_e32 v5, v29, v5
	ds_bpermute_b32 v25, v13, v4
	ds_bpermute_b32 v26, v13, v5
	s_waitcnt lgkmcnt(2)
	v_add_f32_e32 v6, v23, v6
	ds_bpermute_b32 v23, v13, v6
	ds_bpermute_b32 v29, v28, v16
	s_waitcnt lgkmcnt(3)
	v_add_f32_e32 v4, v4, v25
	s_waitcnt lgkmcnt(2)
	v_add_f32_e32 v5, v5, v26
	ds_bpermute_b32 v25, v14, v4
	ds_bpermute_b32 v26, v14, v5
	s_waitcnt lgkmcnt(3)
	v_add_f32_e32 v6, v6, v23
	ds_bpermute_b32 v23, v14, v6
	s_waitcnt lgkmcnt(2)
	v_add_f32_e32 v25, v4, v25
	s_waitcnt lgkmcnt(1)
	v_add_f32_e32 v5, v5, v26
	ds_bpermute_b32 v26, v15, v25
	v_lshlrev_b32_e32 v4, 16, v21
	s_waitcnt lgkmcnt(1)
	v_add_f32_e32 v6, v6, v23
	ds_bpermute_b32 v23, v15, v5
	ds_bpermute_b32 v31, v15, v6
	s_waitcnt lgkmcnt(2)
	v_add_f32_e32 v21, v25, v26
	ds_bpermute_b32 v25, v28, v21
	s_waitcnt lgkmcnt(2)
	v_add_f32_e32 v5, v5, v23
	ds_bpermute_b32 v23, v28, v5
	s_waitcnt lgkmcnt(2)
	v_add_f32_e32 v6, v6, v31
	s_waitcnt lgkmcnt(1)
	v_add_f32_e32 v21, v21, v25
	v_max_f32_e32 v17, v21, v17
	v_max3_f32 v29, v16, v29, v17
	v_sub_f32_e32 v16, v96, v29
	v_sub_f32_e32 v9, v9, v29
	v_mul_f32_e32 v16, 0x3fb8aa3b, v16
	v_mul_f32_e32 v9, 0x3fb8aa3b, v9
	v_exp_f32_e32 v17, v16
	v_exp_f32_e32 v9, v9
	s_waitcnt lgkmcnt(0)
	v_add_f32_e32 v5, v5, v23
	v_max_f32_e32 v16, v5, v18
	v_max3_f32 v30, v24, v30, v16
	v_add_f32_e32 v16, v17, v9
	ds_bpermute_b32 v18, v19, v16
	v_sub_f32_e32 v23, v95, v30
	v_sub_f32_e32 v10, v10, v30
	v_mul_f32_e32 v23, 0x3fb8aa3b, v23
	v_mul_f32_e32 v10, 0x3fb8aa3b, v10
	s_waitcnt lgkmcnt(0)
	v_add_f32_e32 v16, v16, v18
	ds_bpermute_b32 v18, v20, v16
	v_exp_f32_e32 v23, v23
	v_exp_f32_e32 v10, v10
	v_sub_f32_e32 v21, v21, v29
	v_mul_f32_e32 v21, 0x3fb8aa3b, v21
	s_waitcnt lgkmcnt(0)
	v_add_f32_e32 v16, v16, v18
	ds_bpermute_b32 v18, v13, v16
	v_add_f32_e32 v24, v23, v10
	ds_bpermute_b32 v25, v19, v24
	ds_write2st64_b32 v71, v17, v9 offset0:4 offset1:5
	ds_bpermute_b32 v26, v28, v6
	s_waitcnt lgkmcnt(3)
	v_add_f32_e32 v18, v16, v18
	ds_bpermute_b32 v31, v14, v18
	s_waitcnt lgkmcnt(3)
	v_add_f32_e32 v9, v24, v25
	v_exp_f32_e32 v16, v21
	ds_bpermute_b32 v21, v20, v9
	v_sub_f32_e32 v5, v5, v30
	s_waitcnt lgkmcnt(1)
	v_add_f32_e32 v31, v18, v31
	v_max_f32_e32 v18, v22, v27
	ds_bpermute_b32 v22, v15, v18
	v_mul_f32_e32 v5, 0x3fb8aa3b, v5
	v_mul_f32_e32 v24, v7, v12
	v_max_f32_e32 v25, v93, v8
	v_exp_f32_e32 v17, v5
	s_waitcnt lgkmcnt(1)
	v_add_f32_e32 v5, v9, v21
	v_add_f32_e32 v6, v6, v26
	s_waitcnt lgkmcnt(0)
	v_max_f32_e32 v21, v22, v22
	ds_bpermute_b32 v24, v19, v24
	ds_bpermute_b32 v26, v19, v25
	v_max_f32_e32 v18, v18, v21
	ds_bpermute_b32 v21, v28, v18
	v_max_f32_e32 v22, v2, v2
	s_waitcnt lgkmcnt(2)
	v_fmac_f32_e32 v24, v7, v12
	s_waitcnt lgkmcnt(1)
	v_max_f32_e32 v12, v26, v26
	v_max_f32_e32 v22, v6, v22
	v_max_f32_e32 v12, v25, v12
	s_waitcnt lgkmcnt(0)
	v_max3_f32 v33, v18, v21, v22
	ds_bpermute_b32 v18, v20, v12
	ds_bpermute_b32 v7, v20, v24
	v_sub_f32_e32 v21, v94, v33
	v_sub_f32_e32 v11, v11, v33
	ds_bpermute_b32 v9, v13, v5
	s_waitcnt lgkmcnt(2)
	v_max_f32_e32 v18, v18, v18
	v_max_f32_e32 v12, v12, v18
	s_waitcnt lgkmcnt(1)
	v_add_f32_e32 v7, v24, v7
	ds_bpermute_b32 v18, v13, v12
	ds_bpermute_b32 v22, v13, v7
	v_mul_f32_e32 v21, 0x3fb8aa3b, v21
	v_mul_f32_e32 v11, 0x3fb8aa3b, v11
	v_exp_f32_e32 v21, v21
	s_waitcnt lgkmcnt(1)
	v_max_f32_e32 v18, v18, v18
	s_waitcnt lgkmcnt(0)
	v_add_f32_e32 v7, v7, v22
	v_max_f32_e32 v12, v12, v18
	ds_bpermute_b32 v22, v14, v7
	ds_bpermute_b32 v18, v14, v12
	v_exp_f32_e32 v11, v11
	v_add_f32_e32 v5, v5, v9
	ds_write2st64_b32 v85, v23, v10 offset0:6 offset1:7
	s_waitcnt lgkmcnt(2)
	v_add_f32_e32 v7, v7, v22
	s_waitcnt lgkmcnt(1)
	v_max_f32_e32 v18, v18, v18
	ds_bpermute_b32 v22, v15, v7
	v_max_f32_e32 v12, v12, v18
	ds_bpermute_b32 v18, v15, v12
	v_add_f32_e32 v9, v21, v11
	ds_bpermute_b32 v24, v19, v9
	s_waitcnt lgkmcnt(2)
	v_add_f32_e32 v7, v7, v22
	ds_bpermute_b32 v22, v28, v7
	s_waitcnt lgkmcnt(2)
	v_max_f32_e32 v18, v18, v18
	v_max_f32_e32 v12, v12, v18
	ds_bpermute_b32 v18, v28, v12
	s_waitcnt lgkmcnt(2)
	v_add_f32_e32 v9, v9, v24
	s_waitcnt lgkmcnt(1)
	v_add_f32_e32 v7, v7, v22
	v_max_f32_e32 v22, v3, v3
	v_max_f32_e32 v22, v7, v22
	s_waitcnt lgkmcnt(0)
	v_max3_f32 v34, v12, v18, v22
	v_sub_f32_e32 v12, v93, v34
	v_sub_f32_e32 v8, v8, v34
	v_mul_f32_e32 v12, 0x3fb8aa3b, v12
	v_mul_f32_e32 v8, 0x3fb8aa3b, v8
	v_exp_f32_e32 v12, v12
	v_exp_f32_e32 v8, v8
	ds_bpermute_b32 v18, v14, v5
	ds_bpermute_b32 v22, v20, v9
	v_sub_f32_e32 v6, v6, v33
	v_add_f32_e32 v24, v12, v8
	ds_bpermute_b32 v19, v19, v24
	s_waitcnt lgkmcnt(2)
	v_add_f32_e32 v35, v5, v18
	s_waitcnt lgkmcnt(1)
	v_add_f32_e32 v5, v9, v22
	ds_bpermute_b32 v9, v13, v5
	v_mul_f32_e32 v6, 0x3fb8aa3b, v6
	s_waitcnt lgkmcnt(1)
	v_add_f32_e32 v18, v24, v19
	ds_bpermute_b32 v19, v20, v18
	v_exp_f32_e32 v20, v6
	s_waitcnt lgkmcnt(1)
	v_add_f32_e32 v5, v5, v9
	ds_bpermute_b32 v9, v14, v5
	v_sub_f32_e32 v7, v7, v34
	s_waitcnt lgkmcnt(1)
	v_add_f32_e32 v10, v18, v19
	ds_bpermute_b32 v13, v13, v10
	v_mul_f32_e32 v7, 0x3fb8aa3b, v7
	s_waitcnt lgkmcnt(1)
	v_add_f32_e32 v37, v5, v9
	ds_write2st64_b32 v86, v21, v11 offset0:8 offset1:9
	v_exp_f32_e32 v21, v7
	s_waitcnt lgkmcnt(1)
	v_add_f32_e32 v5, v10, v13
	ds_bpermute_b32 v6, v14, v5
	ds_bpermute_b32 v32, v15, v31
	ds_bpermute_b32 v36, v15, v35
	ds_bpermute_b32 v38, v15, v37
	ds_write2st64_b32 v87, v12, v8 offset0:10 offset1:11
	s_waitcnt lgkmcnt(4)
	v_add_f32_e32 v39, v5, v6
	ds_bpermute_b32 v40, v15, v39
	v_pk_mul_f32 v[22:23], v[20:21], v[4:5] op_sel_hi:[1,0]
	v_pk_mul_f32 v[18:19], v[16:17], v[4:5] op_sel_hi:[1,0]
	s_waitcnt lgkmcnt(0)
	v_lshlrev_b64 v[4:5], 10, v[62:63]
	v_lshl_or_b32 v4, v88, 8, v4
	v_lshl_add_u64 v[24:25], v[56:57], 0, v[4:5]
